# SGU items as per-wave static tasks at the head of phase sp3 (no compiler loop, tickets or barriers left in sp3); chain state tiles transposed (8/16-byte stores)
# speedup vs baseline: 1.0046x; 1.0046x over previous
.Lsp3_entry:
	s_cmpk_ge_u32 s63, 0xc0
	s_cbranch_scc1 .Lsp3_e2
	v_and_b32_e32 v125, 63, v206
	v_lshrrev_b32_e32 v124, 6, v206
	v_and_b32_e32 v120, 15, v125
	v_readfirstlane_b32 s40, v124
	v_lshrrev_b32_e32 v121, 4, v125
	s_lshr_b32 s41, s63, 2
	s_and_b32 s42, s63, 3
	v_lshlrev_b32_e32 v122, 8, v120
	v_lshl_add_u32 v122, v121, 4, v122
	s_lshl_b32 s43, s36, 2
	s_add_u32 s43, s43, s42
	s_lshl_b32 s100, s43, 7
	s_lshl_b32 s101, s40, 4
	s_add_u32 s100, s100, s101
	s_lshl_b32 s100, s100, 8
	s_add_u32 s100, s100, 0x2dc0000
	s_add_u32 s44, s96, s100
	s_addc_u32 s45, s97, 0
	global_load_dwordx4 v[4:7], v122, s[44:45]
	global_load_dwordx4 v[8:11], v122, s[44:45] offset:64
	global_load_dwordx4 v[12:15], v122, s[44:45] offset:128
	global_load_dwordx4 v[16:19], v122, s[44:45] offset:192
	s_lshl_b32 s100, s41, 8
	s_lshl_b32 s101, s42, 6
	s_add_u32 s100, s100, s101
	s_lshl_b32 s100, s100, 8
	s_add_u32 s100, s100, 0xc784000
	s_add_u32 s46, s96, s100
	s_addc_u32 s47, s97, 0
	global_load_dwordx4 v[20:23], v122, s[46:47]
	global_load_dwordx4 v[36:39], v122, s[46:47] offset:64
	global_load_dwordx4 v[52:55], v122, s[46:47] offset:128
	global_load_dwordx4 v[68:71], v122, s[46:47] offset:192
	s_add_u32 s46, s46, 0x1000
	s_addc_u32 s47, s47, 0
	global_load_dwordx4 v[24:27], v122, s[46:47]
	global_load_dwordx4 v[40:43], v122, s[46:47] offset:64
	global_load_dwordx4 v[56:59], v122, s[46:47] offset:128
	global_load_dwordx4 v[72:75], v122, s[46:47] offset:192
	s_add_u32 s46, s46, 0x1000
	s_addc_u32 s47, s47, 0
	global_load_dwordx4 v[28:31], v122, s[46:47]
	global_load_dwordx4 v[44:47], v122, s[46:47] offset:64
	global_load_dwordx4 v[60:63], v122, s[46:47] offset:128
	global_load_dwordx4 v[76:79], v122, s[46:47] offset:192
	s_add_u32 s46, s46, 0x1000
	s_addc_u32 s47, s47, 0
	global_load_dwordx4 v[32:35], v122, s[46:47]
	global_load_dwordx4 v[48:51], v122, s[46:47] offset:64
	global_load_dwordx4 v[64:67], v122, s[46:47] offset:128
	global_load_dwordx4 v[80:83], v122, s[46:47] offset:192
	v_readlane_b32 s48, v237, 33
	v_readlane_b32 s49, v237, 34
	s_lshl_b32 s100, s43, 9
	s_lshl_b32 s101, s40, 6
	s_add_u32 s100, s100, s101
	s_add_u32 s48, s48, s100
	s_addc_u32 s49, s49, 0
	v_lshlrev_b32_e32 v125, 4, v121
	s_nop 0
	global_load_dwordx4 v[100:103], v125, s[48:49]
	s_lshl_b32 s100, s41, 7
	s_lshl_b32 s101, s40, 4
	s_add_u32 s100, s100, s101
	s_mul_i32 s50, s100, 0x2440
	s_lshl_b32 s101, s42, 8
	s_add_u32 s50, s50, s101
	s_add_u32 s50, s50, 0x3a25840
	s_add_u32 s52, s96, s50
	s_addc_u32 s53, s97, 0
	v_mul_u32_u24_e32 v123, 0x9100, v121
	v_lshl_add_u32 v123, v120, 2, v123
	global_load_dword v104, v123, s[52:53]
	global_load_dword v105, v123, s[52:53] offset:64
	global_load_dword v106, v123, s[52:53] offset:128
	global_load_dword v107, v123, s[52:53] offset:192
	v_add_u32_e32 v125, 0x2440, v123
	global_load_dword v108, v125, s[52:53]
	global_load_dword v109, v125, s[52:53] offset:64
	global_load_dword v110, v125, s[52:53] offset:128
	global_load_dword v111, v125, s[52:53] offset:192
	v_add_u32_e32 v125, 0x4880, v123
	global_load_dword v112, v125, s[52:53]
	global_load_dword v113, v125, s[52:53] offset:64
	global_load_dword v114, v125, s[52:53] offset:128
	global_load_dword v115, v125, s[52:53] offset:192
	v_add_u32_e32 v125, 0x6cc0, v123
	global_load_dword v116, v125, s[52:53]
	global_load_dword v117, v125, s[52:53] offset:64
	global_load_dword v118, v125, s[52:53] offset:128
	global_load_dword v119, v125, s[52:53] offset:192
	s_lshl_b32 s50, s100, 11
	s_lshl_b32 s101, s42, 7
	s_add_u32 s50, s50, s101
	s_add_u32 s50, s50, 0x7084400
	s_add_u32 s54, s96, s50
	s_addc_u32 s55, s97, 0
	v_lshlrev_b32_e32 v124, 13, v121
	v_lshl_add_u32 v124, v120, 1, v124
	s_waitcnt vmcnt(17)
	v_mfma_f32_16x16x32_bf16 v[84:87], v[4:7], v[20:23], 0
	v_mfma_f32_16x16x32_bf16 v[88:91], v[4:7], v[24:27], 0
	v_mfma_f32_16x16x32_bf16 v[92:95], v[4:7], v[28:31], 0
	v_mfma_f32_16x16x32_bf16 v[96:99], v[4:7], v[32:35], 0
	v_mfma_f32_16x16x32_bf16 v[84:87], v[8:11], v[36:39], v[84:87]
	v_mfma_f32_16x16x32_bf16 v[88:91], v[8:11], v[40:43], v[88:91]
	v_mfma_f32_16x16x32_bf16 v[92:95], v[8:11], v[44:47], v[92:95]
	v_mfma_f32_16x16x32_bf16 v[96:99], v[8:11], v[48:51], v[96:99]
	v_mfma_f32_16x16x32_bf16 v[84:87], v[12:15], v[52:55], v[84:87]
	v_mfma_f32_16x16x32_bf16 v[88:91], v[12:15], v[56:59], v[88:91]
	v_mfma_f32_16x16x32_bf16 v[92:95], v[12:15], v[60:63], v[92:95]
	v_mfma_f32_16x16x32_bf16 v[96:99], v[12:15], v[64:67], v[96:99]
	v_mfma_f32_16x16x32_bf16 v[84:87], v[16:19], v[68:71], v[84:87]
	v_mfma_f32_16x16x32_bf16 v[88:91], v[16:19], v[72:75], v[88:91]
	v_mfma_f32_16x16x32_bf16 v[92:95], v[16:19], v[76:79], v[92:95]
	v_mfma_f32_16x16x32_bf16 v[96:99], v[16:19], v[80:83], v[96:99]
	s_waitcnt vmcnt(0)
	s_nop 4
	v_mul_f32_e32 v126, 0x3d372713, v104
	v_mul_f32_e32 v126, v104, v126
	v_fma_f32 v126, v104, v126, v104
	v_mul_f32_e32 v126, 0x3f4c422a, v126
	v_add_f32_e32 v126, v126, v126
	v_mul_f32_e32 v126, 0x3fb8aa3b, v126
	v_exp_f32_e32 v126, v126
	v_mul_f32_e32 v127, 0.5, v104
	v_add_f32_e32 v126, 1.0, v126
	v_div_scale_f32 v128, s[100:101], v126, v126, 2.0
	v_rcp_f32_e32 v129, v128
	s_nop 0
	v_fma_f32 v130, -v128, v129, 1.0
	v_fmac_f32_e32 v129, v130, v129
	v_div_scale_f32 v130, vcc, 2.0, v126, 2.0
	v_mul_f32_e32 v131, v130, v129
	v_fma_f32 v132, -v128, v131, v130
	v_fmac_f32_e32 v131, v132, v129
	v_fma_f32 v128, -v128, v131, v130
	v_div_fmas_f32 v128, v128, v129, v131
	v_div_fixup_f32 v126, v128, v126, 2.0
	v_sub_f32_e32 v126, 1.0, v126
	v_add_f32_e32 v126, 1.0, v126
	v_mul_f32_e32 v104, v127, v126
	v_add_f32_e32 v126, v84, v100
	v_mul_f32_e32 v104, v104, v126
	v_bfe_u32 v126, v104, 16, 1
	v_add3_u32 v104, v104, v126, s27
	global_store_short_d16_hi v124, v104, s[54:55]
	v_mul_f32_e32 v126, 0x3d372713, v105
	v_mul_f32_e32 v126, v105, v126
	v_fma_f32 v126, v105, v126, v105
	v_mul_f32_e32 v126, 0x3f4c422a, v126
	v_add_f32_e32 v126, v126, v126
	v_mul_f32_e32 v126, 0x3fb8aa3b, v126
	v_exp_f32_e32 v126, v126
	v_mul_f32_e32 v127, 0.5, v105
	v_add_f32_e32 v126, 1.0, v126
	v_div_scale_f32 v128, s[100:101], v126, v126, 2.0
	v_rcp_f32_e32 v129, v128
	s_nop 0
	v_fma_f32 v130, -v128, v129, 1.0
	v_fmac_f32_e32 v129, v130, v129
	v_div_scale_f32 v130, vcc, 2.0, v126, 2.0
	v_mul_f32_e32 v131, v130, v129
	v_fma_f32 v132, -v128, v131, v130
	v_fmac_f32_e32 v131, v132, v129
	v_fma_f32 v128, -v128, v131, v130
	v_div_fmas_f32 v128, v128, v129, v131
	v_div_fixup_f32 v126, v128, v126, 2.0
	v_sub_f32_e32 v126, 1.0, v126
	v_add_f32_e32 v126, 1.0, v126
	v_mul_f32_e32 v105, v127, v126
	v_add_f32_e32 v126, v88, v100
	v_mul_f32_e32 v105, v105, v126
	v_bfe_u32 v126, v105, 16, 1
	v_add3_u32 v105, v105, v126, s27
	global_store_short_d16_hi v124, v105, s[54:55] offset:32
	v_mul_f32_e32 v126, 0x3d372713, v106
	v_mul_f32_e32 v126, v106, v126
	v_fma_f32 v126, v106, v126, v106
	v_mul_f32_e32 v126, 0x3f4c422a, v126
	v_add_f32_e32 v126, v126, v126
	v_mul_f32_e32 v126, 0x3fb8aa3b, v126
	v_exp_f32_e32 v126, v126
	v_mul_f32_e32 v127, 0.5, v106
	v_add_f32_e32 v126, 1.0, v126
	v_div_scale_f32 v128, s[100:101], v126, v126, 2.0
	v_rcp_f32_e32 v129, v128
	s_nop 0
	v_fma_f32 v130, -v128, v129, 1.0
	v_fmac_f32_e32 v129, v130, v129
	v_div_scale_f32 v130, vcc, 2.0, v126, 2.0
	v_mul_f32_e32 v131, v130, v129
	v_fma_f32 v132, -v128, v131, v130
	v_fmac_f32_e32 v131, v132, v129
	v_fma_f32 v128, -v128, v131, v130
	v_div_fmas_f32 v128, v128, v129, v131
	v_div_fixup_f32 v126, v128, v126, 2.0
	v_sub_f32_e32 v126, 1.0, v126
	v_add_f32_e32 v126, 1.0, v126
	v_mul_f32_e32 v106, v127, v126
	v_add_f32_e32 v126, v92, v100
	v_mul_f32_e32 v106, v106, v126
	v_bfe_u32 v126, v106, 16, 1
	v_add3_u32 v106, v106, v126, s27
	global_store_short_d16_hi v124, v106, s[54:55] offset:64
	v_mul_f32_e32 v126, 0x3d372713, v107
	v_mul_f32_e32 v126, v107, v126
	v_fma_f32 v126, v107, v126, v107
	v_mul_f32_e32 v126, 0x3f4c422a, v126
	v_add_f32_e32 v126, v126, v126
	v_mul_f32_e32 v126, 0x3fb8aa3b, v126
	v_exp_f32_e32 v126, v126
	v_mul_f32_e32 v127, 0.5, v107
	v_add_f32_e32 v126, 1.0, v126
	v_div_scale_f32 v128, s[100:101], v126, v126, 2.0
	v_rcp_f32_e32 v129, v128
	s_nop 0
	v_fma_f32 v130, -v128, v129, 1.0
	v_fmac_f32_e32 v129, v130, v129
	v_div_scale_f32 v130, vcc, 2.0, v126, 2.0
	v_mul_f32_e32 v131, v130, v129
	v_fma_f32 v132, -v128, v131, v130
	v_fmac_f32_e32 v131, v132, v129
	v_fma_f32 v128, -v128, v131, v130
	v_div_fmas_f32 v128, v128, v129, v131
	v_div_fixup_f32 v126, v128, v126, 2.0
	v_sub_f32_e32 v126, 1.0, v126
	v_add_f32_e32 v126, 1.0, v126
	v_mul_f32_e32 v107, v127, v126
	v_add_f32_e32 v126, v96, v100
	v_mul_f32_e32 v107, v107, v126
	v_bfe_u32 v126, v107, 16, 1
	v_add3_u32 v107, v107, v126, s27
	global_store_short_d16_hi v124, v107, s[54:55] offset:96
	v_add_u32_e32 v125, 0x800, v124
	v_mul_f32_e32 v126, 0x3d372713, v108
	v_mul_f32_e32 v126, v108, v126
	v_fma_f32 v126, v108, v126, v108
	v_mul_f32_e32 v126, 0x3f4c422a, v126
	v_add_f32_e32 v126, v126, v126
	v_mul_f32_e32 v126, 0x3fb8aa3b, v126
	v_exp_f32_e32 v126, v126
	v_mul_f32_e32 v127, 0.5, v108
	v_add_f32_e32 v126, 1.0, v126
	v_div_scale_f32 v128, s[100:101], v126, v126, 2.0
	v_rcp_f32_e32 v129, v128
	s_nop 0
	v_fma_f32 v130, -v128, v129, 1.0
	v_fmac_f32_e32 v129, v130, v129
	v_div_scale_f32 v130, vcc, 2.0, v126, 2.0
	v_mul_f32_e32 v131, v130, v129
	v_fma_f32 v132, -v128, v131, v130
	v_fmac_f32_e32 v131, v132, v129
	v_fma_f32 v128, -v128, v131, v130
	v_div_fmas_f32 v128, v128, v129, v131
	v_div_fixup_f32 v126, v128, v126, 2.0
	v_sub_f32_e32 v126, 1.0, v126
	v_add_f32_e32 v126, 1.0, v126
	v_mul_f32_e32 v108, v127, v126
	v_add_f32_e32 v126, v85, v101
	v_mul_f32_e32 v108, v108, v126
	v_bfe_u32 v126, v108, 16, 1
	v_add3_u32 v108, v108, v126, s27
	global_store_short_d16_hi v125, v108, s[54:55]
	v_mul_f32_e32 v126, 0x3d372713, v109
	v_mul_f32_e32 v126, v109, v126
	v_fma_f32 v126, v109, v126, v109
	v_mul_f32_e32 v126, 0x3f4c422a, v126
	v_add_f32_e32 v126, v126, v126
	v_mul_f32_e32 v126, 0x3fb8aa3b, v126
	v_exp_f32_e32 v126, v126
	v_mul_f32_e32 v127, 0.5, v109
	v_add_f32_e32 v126, 1.0, v126
	v_div_scale_f32 v128, s[100:101], v126, v126, 2.0
	v_rcp_f32_e32 v129, v128
	s_nop 0
	v_fma_f32 v130, -v128, v129, 1.0
	v_fmac_f32_e32 v129, v130, v129
	v_div_scale_f32 v130, vcc, 2.0, v126, 2.0
	v_mul_f32_e32 v131, v130, v129
	v_fma_f32 v132, -v128, v131, v130
	v_fmac_f32_e32 v131, v132, v129
	v_fma_f32 v128, -v128, v131, v130
	v_div_fmas_f32 v128, v128, v129, v131
	v_div_fixup_f32 v126, v128, v126, 2.0
	v_sub_f32_e32 v126, 1.0, v126
	v_add_f32_e32 v126, 1.0, v126
	v_mul_f32_e32 v109, v127, v126
	v_add_f32_e32 v126, v89, v101
	v_mul_f32_e32 v109, v109, v126
	v_bfe_u32 v126, v109, 16, 1
	v_add3_u32 v109, v109, v126, s27
	global_store_short_d16_hi v125, v109, s[54:55] offset:32
	v_mul_f32_e32 v126, 0x3d372713, v110
	v_mul_f32_e32 v126, v110, v126
	v_fma_f32 v126, v110, v126, v110
	v_mul_f32_e32 v126, 0x3f4c422a, v126
	v_add_f32_e32 v126, v126, v126
	v_mul_f32_e32 v126, 0x3fb8aa3b, v126
	v_exp_f32_e32 v126, v126
	v_mul_f32_e32 v127, 0.5, v110
	v_add_f32_e32 v126, 1.0, v126
	v_div_scale_f32 v128, s[100:101], v126, v126, 2.0
	v_rcp_f32_e32 v129, v128
	s_nop 0
	v_fma_f32 v130, -v128, v129, 1.0
	v_fmac_f32_e32 v129, v130, v129
	v_div_scale_f32 v130, vcc, 2.0, v126, 2.0
	v_mul_f32_e32 v131, v130, v129
	v_fma_f32 v132, -v128, v131, v130
	v_fmac_f32_e32 v131, v132, v129
	v_fma_f32 v128, -v128, v131, v130
	v_div_fmas_f32 v128, v128, v129, v131
	v_div_fixup_f32 v126, v128, v126, 2.0
	v_sub_f32_e32 v126, 1.0, v126
	v_add_f32_e32 v126, 1.0, v126
	v_mul_f32_e32 v110, v127, v126
	v_add_f32_e32 v126, v93, v101
	v_mul_f32_e32 v110, v110, v126
	v_bfe_u32 v126, v110, 16, 1
	v_add3_u32 v110, v110, v126, s27
	global_store_short_d16_hi v125, v110, s[54:55] offset:64
	v_mul_f32_e32 v126, 0x3d372713, v111
	v_mul_f32_e32 v126, v111, v126
	v_fma_f32 v126, v111, v126, v111
	v_mul_f32_e32 v126, 0x3f4c422a, v126
	v_add_f32_e32 v126, v126, v126
	v_mul_f32_e32 v126, 0x3fb8aa3b, v126
	v_exp_f32_e32 v126, v126
	v_mul_f32_e32 v127, 0.5, v111
	v_add_f32_e32 v126, 1.0, v126
	v_div_scale_f32 v128, s[100:101], v126, v126, 2.0
	v_rcp_f32_e32 v129, v128
	s_nop 0
	v_fma_f32 v130, -v128, v129, 1.0
	v_fmac_f32_e32 v129, v130, v129
	v_div_scale_f32 v130, vcc, 2.0, v126, 2.0
	v_mul_f32_e32 v131, v130, v129
	v_fma_f32 v132, -v128, v131, v130
	v_fmac_f32_e32 v131, v132, v129
	v_fma_f32 v128, -v128, v131, v130
	v_div_fmas_f32 v128, v128, v129, v131
	v_div_fixup_f32 v126, v128, v126, 2.0
	v_sub_f32_e32 v126, 1.0, v126
	v_add_f32_e32 v126, 1.0, v126
	v_mul_f32_e32 v111, v127, v126
	v_add_f32_e32 v126, v97, v101
	v_mul_f32_e32 v111, v111, v126
	v_bfe_u32 v126, v111, 16, 1
	v_add3_u32 v111, v111, v126, s27
	global_store_short_d16_hi v125, v111, s[54:55] offset:96
	v_add_u32_e32 v125, 0x1000, v124
	v_mul_f32_e32 v126, 0x3d372713, v112
	v_mul_f32_e32 v126, v112, v126
	v_fma_f32 v126, v112, v126, v112
	v_mul_f32_e32 v126, 0x3f4c422a, v126
	v_add_f32_e32 v126, v126, v126
	v_mul_f32_e32 v126, 0x3fb8aa3b, v126
	v_exp_f32_e32 v126, v126
	v_mul_f32_e32 v127, 0.5, v112
	v_add_f32_e32 v126, 1.0, v126
	v_div_scale_f32 v128, s[100:101], v126, v126, 2.0
	v_rcp_f32_e32 v129, v128
	s_nop 0
	v_fma_f32 v130, -v128, v129, 1.0
	v_fmac_f32_e32 v129, v130, v129
	v_div_scale_f32 v130, vcc, 2.0, v126, 2.0
	v_mul_f32_e32 v131, v130, v129
	v_fma_f32 v132, -v128, v131, v130
	v_fmac_f32_e32 v131, v132, v129
	v_fma_f32 v128, -v128, v131, v130
	v_div_fmas_f32 v128, v128, v129, v131
	v_div_fixup_f32 v126, v128, v126, 2.0
	v_sub_f32_e32 v126, 1.0, v126
	v_add_f32_e32 v126, 1.0, v126
	v_mul_f32_e32 v112, v127, v126
	v_add_f32_e32 v126, v86, v102
	v_mul_f32_e32 v112, v112, v126
	v_bfe_u32 v126, v112, 16, 1
	v_add3_u32 v112, v112, v126, s27
	global_store_short_d16_hi v125, v112, s[54:55]
	v_mul_f32_e32 v126, 0x3d372713, v113
	v_mul_f32_e32 v126, v113, v126
	v_fma_f32 v126, v113, v126, v113
	v_mul_f32_e32 v126, 0x3f4c422a, v126
	v_add_f32_e32 v126, v126, v126
	v_mul_f32_e32 v126, 0x3fb8aa3b, v126
	v_exp_f32_e32 v126, v126
	v_mul_f32_e32 v127, 0.5, v113
	v_add_f32_e32 v126, 1.0, v126
	v_div_scale_f32 v128, s[100:101], v126, v126, 2.0
	v_rcp_f32_e32 v129, v128
	s_nop 0
	v_fma_f32 v130, -v128, v129, 1.0
	v_fmac_f32_e32 v129, v130, v129
	v_div_scale_f32 v130, vcc, 2.0, v126, 2.0
	v_mul_f32_e32 v131, v130, v129
	v_fma_f32 v132, -v128, v131, v130
	v_fmac_f32_e32 v131, v132, v129
	v_fma_f32 v128, -v128, v131, v130
	v_div_fmas_f32 v128, v128, v129, v131
	v_div_fixup_f32 v126, v128, v126, 2.0
	v_sub_f32_e32 v126, 1.0, v126
	v_add_f32_e32 v126, 1.0, v126
	v_mul_f32_e32 v113, v127, v126
	v_add_f32_e32 v126, v90, v102
	v_mul_f32_e32 v113, v113, v126
	v_bfe_u32 v126, v113, 16, 1
	v_add3_u32 v113, v113, v126, s27
	global_store_short_d16_hi v125, v113, s[54:55] offset:32
	v_mul_f32_e32 v126, 0x3d372713, v114
	v_mul_f32_e32 v126, v114, v126
	v_fma_f32 v126, v114, v126, v114
	v_mul_f32_e32 v126, 0x3f4c422a, v126
	v_add_f32_e32 v126, v126, v126
	v_mul_f32_e32 v126, 0x3fb8aa3b, v126
	v_exp_f32_e32 v126, v126
	v_mul_f32_e32 v127, 0.5, v114
	v_add_f32_e32 v126, 1.0, v126
	v_div_scale_f32 v128, s[100:101], v126, v126, 2.0
	v_rcp_f32_e32 v129, v128
	s_nop 0
	v_fma_f32 v130, -v128, v129, 1.0
	v_fmac_f32_e32 v129, v130, v129
	v_div_scale_f32 v130, vcc, 2.0, v126, 2.0
	v_mul_f32_e32 v131, v130, v129
	v_fma_f32 v132, -v128, v131, v130
	v_fmac_f32_e32 v131, v132, v129
	v_fma_f32 v128, -v128, v131, v130
	v_div_fmas_f32 v128, v128, v129, v131
	v_div_fixup_f32 v126, v128, v126, 2.0
	v_sub_f32_e32 v126, 1.0, v126
	v_add_f32_e32 v126, 1.0, v126
	v_mul_f32_e32 v114, v127, v126
	v_add_f32_e32 v126, v94, v102
	v_mul_f32_e32 v114, v114, v126
	v_bfe_u32 v126, v114, 16, 1
	v_add3_u32 v114, v114, v126, s27
	global_store_short_d16_hi v125, v114, s[54:55] offset:64
	v_mul_f32_e32 v126, 0x3d372713, v115
	v_mul_f32_e32 v126, v115, v126
	v_fma_f32 v126, v115, v126, v115
	v_mul_f32_e32 v126, 0x3f4c422a, v126
	v_add_f32_e32 v126, v126, v126
	v_mul_f32_e32 v126, 0x3fb8aa3b, v126
	v_exp_f32_e32 v126, v126
	v_mul_f32_e32 v127, 0.5, v115
	v_add_f32_e32 v126, 1.0, v126
	v_div_scale_f32 v128, s[100:101], v126, v126, 2.0
	v_rcp_f32_e32 v129, v128
	s_nop 0
	v_fma_f32 v130, -v128, v129, 1.0
	v_fmac_f32_e32 v129, v130, v129
	v_div_scale_f32 v130, vcc, 2.0, v126, 2.0
	v_mul_f32_e32 v131, v130, v129
	v_fma_f32 v132, -v128, v131, v130
	v_fmac_f32_e32 v131, v132, v129
	v_fma_f32 v128, -v128, v131, v130
	v_div_fmas_f32 v128, v128, v129, v131
	v_div_fixup_f32 v126, v128, v126, 2.0
	v_sub_f32_e32 v126, 1.0, v126
	v_add_f32_e32 v126, 1.0, v126
	v_mul_f32_e32 v115, v127, v126
	v_add_f32_e32 v126, v98, v102
	v_mul_f32_e32 v115, v115, v126
	v_bfe_u32 v126, v115, 16, 1
	v_add3_u32 v115, v115, v126, s27
	global_store_short_d16_hi v125, v115, s[54:55] offset:96
	v_add_u32_e32 v125, 0x1800, v124
	v_mul_f32_e32 v126, 0x3d372713, v116
	v_mul_f32_e32 v126, v116, v126
	v_fma_f32 v126, v116, v126, v116
	v_mul_f32_e32 v126, 0x3f4c422a, v126
	v_add_f32_e32 v126, v126, v126
	v_mul_f32_e32 v126, 0x3fb8aa3b, v126
	v_exp_f32_e32 v126, v126
	v_mul_f32_e32 v127, 0.5, v116
	v_add_f32_e32 v126, 1.0, v126
	v_div_scale_f32 v128, s[100:101], v126, v126, 2.0
	v_rcp_f32_e32 v129, v128
	s_nop 0
	v_fma_f32 v130, -v128, v129, 1.0
	v_fmac_f32_e32 v129, v130, v129
	v_div_scale_f32 v130, vcc, 2.0, v126, 2.0
	v_mul_f32_e32 v131, v130, v129
	v_fma_f32 v132, -v128, v131, v130
	v_fmac_f32_e32 v131, v132, v129
	v_fma_f32 v128, -v128, v131, v130
	v_div_fmas_f32 v128, v128, v129, v131
	v_div_fixup_f32 v126, v128, v126, 2.0
	v_sub_f32_e32 v126, 1.0, v126
	v_add_f32_e32 v126, 1.0, v126
	v_mul_f32_e32 v116, v127, v126
	v_add_f32_e32 v126, v87, v103
	v_mul_f32_e32 v116, v116, v126
	v_bfe_u32 v126, v116, 16, 1
	v_add3_u32 v116, v116, v126, s27
	global_store_short_d16_hi v125, v116, s[54:55]
	v_mul_f32_e32 v126, 0x3d372713, v117
	v_mul_f32_e32 v126, v117, v126
	v_fma_f32 v126, v117, v126, v117
	v_mul_f32_e32 v126, 0x3f4c422a, v126
	v_add_f32_e32 v126, v126, v126
	v_mul_f32_e32 v126, 0x3fb8aa3b, v126
	v_exp_f32_e32 v126, v126
	v_mul_f32_e32 v127, 0.5, v117
	v_add_f32_e32 v126, 1.0, v126
	v_div_scale_f32 v128, s[100:101], v126, v126, 2.0
	v_rcp_f32_e32 v129, v128
	s_nop 0
	v_fma_f32 v130, -v128, v129, 1.0
	v_fmac_f32_e32 v129, v130, v129
	v_div_scale_f32 v130, vcc, 2.0, v126, 2.0
	v_mul_f32_e32 v131, v130, v129
	v_fma_f32 v132, -v128, v131, v130
	v_fmac_f32_e32 v131, v132, v129
	v_fma_f32 v128, -v128, v131, v130
	v_div_fmas_f32 v128, v128, v129, v131
	v_div_fixup_f32 v126, v128, v126, 2.0
	v_sub_f32_e32 v126, 1.0, v126
	v_add_f32_e32 v126, 1.0, v126
	v_mul_f32_e32 v117, v127, v126
	v_add_f32_e32 v126, v91, v103
	v_mul_f32_e32 v117, v117, v126
	v_bfe_u32 v126, v117, 16, 1
	v_add3_u32 v117, v117, v126, s27
	global_store_short_d16_hi v125, v117, s[54:55] offset:32
	v_mul_f32_e32 v126, 0x3d372713, v118
	v_mul_f32_e32 v126, v118, v126
	v_fma_f32 v126, v118, v126, v118
	v_mul_f32_e32 v126, 0x3f4c422a, v126
	v_add_f32_e32 v126, v126, v126
	v_mul_f32_e32 v126, 0x3fb8aa3b, v126
	v_exp_f32_e32 v126, v126
	v_mul_f32_e32 v127, 0.5, v118
	v_add_f32_e32 v126, 1.0, v126
	v_div_scale_f32 v128, s[100:101], v126, v126, 2.0
	v_rcp_f32_e32 v129, v128
	s_nop 0
	v_fma_f32 v130, -v128, v129, 1.0
	v_fmac_f32_e32 v129, v130, v129
	v_div_scale_f32 v130, vcc, 2.0, v126, 2.0
	v_mul_f32_e32 v131, v130, v129
	v_fma_f32 v132, -v128, v131, v130
	v_fmac_f32_e32 v131, v132, v129
	v_fma_f32 v128, -v128, v131, v130
	v_div_fmas_f32 v128, v128, v129, v131
	v_div_fixup_f32 v126, v128, v126, 2.0
	v_sub_f32_e32 v126, 1.0, v126
	v_add_f32_e32 v126, 1.0, v126
	v_mul_f32_e32 v118, v127, v126
	v_add_f32_e32 v126, v95, v103
	v_mul_f32_e32 v118, v118, v126
	v_bfe_u32 v126, v118, 16, 1
	v_add3_u32 v118, v118, v126, s27
	global_store_short_d16_hi v125, v118, s[54:55] offset:64
	v_mul_f32_e32 v126, 0x3d372713, v119
	v_mul_f32_e32 v126, v119, v126
	v_fma_f32 v126, v119, v126, v119
	v_mul_f32_e32 v126, 0x3f4c422a, v126
	v_add_f32_e32 v126, v126, v126
	v_mul_f32_e32 v126, 0x3fb8aa3b, v126
	v_exp_f32_e32 v126, v126
	v_mul_f32_e32 v127, 0.5, v119
	v_add_f32_e32 v126, 1.0, v126
	v_div_scale_f32 v128, s[100:101], v126, v126, 2.0
	v_rcp_f32_e32 v129, v128
	s_nop 0
	v_fma_f32 v130, -v128, v129, 1.0
	v_fmac_f32_e32 v129, v130, v129
	v_div_scale_f32 v130, vcc, 2.0, v126, 2.0
	v_mul_f32_e32 v131, v130, v129
	v_fma_f32 v132, -v128, v131, v130
	v_fmac_f32_e32 v131, v132, v129
	v_fma_f32 v128, -v128, v131, v130
	v_div_fmas_f32 v128, v128, v129, v131
	v_div_fixup_f32 v126, v128, v126, 2.0
	v_sub_f32_e32 v126, 1.0, v126
	v_add_f32_e32 v126, 1.0, v126
	v_mul_f32_e32 v119, v127, v126
	v_add_f32_e32 v126, v99, v103
	v_mul_f32_e32 v119, v119, v126
	v_bfe_u32 v126, v119, 16, 1
	v_add3_u32 v119, v119, v126, s27
	global_store_short_d16_hi v125, v119, s[54:55] offset:96
	s_branch .Lsp3_e2

.Lch_slat_fw:
	v_lshrrev_b32_e32 v167, 5, v165
	v_and_b32_e32 v168, 31, v165
	v_lshlrev_b32_e32 v167, 13, v167
	v_lshl_add_u32 v167, v168, 4, v167
	s_mul_i32 s53, s40, 16896
	s_lshl_b32 s100, s51, 1
	s_add_u32 m0, s53, 0x0
	s_nop 0
	global_load_lds_dwordx4 v167, s[58:59]
	s_add_u32 s58, s58, s100
	s_addc_u32 s59, s59, s92
	s_add_u32 m0, s53, 0x400
	s_nop 0
	global_load_lds_dwordx4 v167, s[58:59]
	s_add_u32 s58, s58, s100
	s_addc_u32 s59, s59, s92
	s_add_u32 m0, s53, 0x800
	s_nop 0
	global_load_lds_dwordx4 v167, s[58:59]
	s_add_u32 s58, s58, s100
	s_addc_u32 s59, s59, s92
	s_add_u32 m0, s53, 0xc00
	s_nop 0
	global_load_lds_dwordx4 v167, s[58:59]
	v_lshlrev_b32_e32 v160, 8, v0
	v_lshl_add_u32 v160, v1, 4, v160
	v_lshlrev_b32_e32 v161, 9, v0
	v_lshl_add_u32 v161, v1, 4, v161
	v_lshrrev_b32_e32 v162, 1, v161
	v_lshl_add_u32 v163, v1, 5, s53
	s_lshl_b32 s100, s52, 15
	s_lshl_b32 s53, s42, 13
	s_add_u32 s100, s100, s53
	s_lshl_b32 s53, s43, 6
	s_add_u32 s100, s100, s53
	s_add_u32 s58, s72, s100
	s_addc_u32 s59, s73, 0
	global_load_dwordx4 v[156:159], v161, s[58:59]
	global_load_dwordx4 v[4:7], v160, s[44:45]
	global_load_dwordx4 v[8:11], v160, s[44:45] offset:64
	global_load_dwordx4 v[12:15], v160, s[44:45] offset:128
	global_load_dwordx4 v[16:19], v160, s[44:45] offset:192
	global_load_dwordx4 v[20:23], v160, s[46:47]
	global_load_dwordx4 v[24:27], v160, s[46:47] offset:64
	global_load_dwordx4 v[28:31], v160, s[46:47] offset:128
	global_load_dwordx4 v[32:35], v160, s[46:47] offset:192
	s_add_u32 s44, s44, s98
	s_addc_u32 s45, s45, s92
	s_add_u32 s46, s46, s99
	s_addc_u32 s47, s47, s92
	global_load_dwordx4 v[36:39], v160, s[44:45]
	global_load_dwordx4 v[40:43], v160, s[44:45] offset:64
	global_load_dwordx4 v[44:47], v160, s[44:45] offset:128
	global_load_dwordx4 v[48:51], v160, s[44:45] offset:192
	global_load_dwordx4 v[52:55], v160, s[46:47]
	global_load_dwordx4 v[56:59], v160, s[46:47] offset:64
	global_load_dwordx4 v[60:63], v160, s[46:47] offset:128
	global_load_dwordx4 v[64:67], v160, s[46:47] offset:192
	s_add_u32 s44, s44, s98
	s_addc_u32 s45, s45, s92
	s_add_u32 s46, s46, s99
	s_addc_u32 s47, s47, s92
	global_load_dwordx4 v[68:71], v160, s[44:45]
	global_load_dwordx4 v[72:75], v160, s[44:45] offset:64
	global_load_dwordx4 v[76:79], v160, s[44:45] offset:128
	global_load_dwordx4 v[80:83], v160, s[44:45] offset:192
	global_load_dwordx4 v[84:87], v160, s[46:47]
	global_load_dwordx4 v[88:91], v160, s[46:47] offset:64
	global_load_dwordx4 v[92:95], v160, s[46:47] offset:128
	global_load_dwordx4 v[96:99], v160, s[46:47] offset:192
	s_add_u32 s44, s44, s98
	s_addc_u32 s45, s45, s92
	s_add_u32 s46, s46, s99
	s_addc_u32 s47, s47, s92
	global_load_dwordx4 v[100:103], v160, s[44:45]
	global_load_dwordx4 v[104:107], v160, s[44:45] offset:64
	global_load_dwordx4 v[108:111], v160, s[44:45] offset:128
	global_load_dwordx4 v[112:115], v160, s[44:45] offset:192
	global_load_dwordx4 v[116:119], v160, s[46:47]
	global_load_dwordx4 v[120:123], v160, s[46:47] offset:64
	global_load_dwordx4 v[124:127], v160, s[46:47] offset:128
	global_load_dwordx4 v[128:131], v160, s[46:47] offset:192
	s_add_u32 s44, s44, s98
	s_addc_u32 s45, s45, s92
	s_add_u32 s46, s46, s99
	s_addc_u32 s47, s47, s92
	s_waitcnt vmcnt(24)
	s_xor_b32 s100, s39, 0
	s_lshl_b32 s100, s100, 9
	v_add_u32_e32 v170, s100, v163
	s_nop 0
	ds_read_b128 v[132:135], v170
	ds_read_b128 v[136:139], v170 offset:16
	v_cvt_pk_bf16_f32 v166, v156, v157
	v_cvt_pk_bf16_f32 v167, v158, v159
	global_store_dwordx2 v162, v[166:167], s[48:49]
	s_nop 0
	s_add_u32 s48, s48, s50
	s_addc_u32 s49, s49, s92
	v_mul_f32_e32 v164, 0x3fb8aa3b, v171
	v_exp_f32_e32 v164, v164
	s_nop 0
	v_mul_f32_e32 v156, v156, v164
	v_mul_f32_e32 v157, v157, v164
	v_mul_f32_e32 v158, v158, v164
	v_mul_f32_e32 v159, v159, v164
	ds_read_b128 v[140:143], v170 offset:128
	ds_read_b128 v[144:147], v170 offset:144
	s_waitcnt lgkmcnt(2)
	v_lshlrev_b32_e32 v165, 16, v4
	v_and_b32_e32 v166, s28, v4
	v_mul_f32_e32 v165, v165, v132
	v_mul_f32_e32 v166, v166, v133
	v_cvt_pk_bf16_f32 v148, v165, v166
	v_lshlrev_b32_e32 v165, 16, v5
	v_and_b32_e32 v166, s28, v5
	v_mul_f32_e32 v165, v165, v134
	v_mul_f32_e32 v166, v166, v135
	v_cvt_pk_bf16_f32 v149, v165, v166
	v_lshlrev_b32_e32 v165, 16, v6
	v_and_b32_e32 v166, s28, v6
	v_mul_f32_e32 v165, v165, v136
	v_mul_f32_e32 v166, v166, v137
	v_cvt_pk_bf16_f32 v150, v165, v166
	v_lshlrev_b32_e32 v165, 16, v7
	v_and_b32_e32 v166, s28, v7
	v_mul_f32_e32 v165, v165, v138
	v_mul_f32_e32 v166, v166, v139
	v_cvt_pk_bf16_f32 v151, v165, v166
	s_nop 1
	v_mfma_f32_16x16x32_bf16 v[156:159], v[20:23], v[148:151], v[156:159]
	ds_read_b128 v[132:135], v170 offset:256
	ds_read_b128 v[136:139], v170 offset:272
	s_waitcnt lgkmcnt(2)
	v_lshlrev_b32_e32 v165, 16, v8
	v_and_b32_e32 v166, s28, v8
	v_mul_f32_e32 v165, v165, v140
	v_mul_f32_e32 v166, v166, v141
	v_cvt_pk_bf16_f32 v152, v165, v166
	v_lshlrev_b32_e32 v165, 16, v9
	v_and_b32_e32 v166, s28, v9
	v_mul_f32_e32 v165, v165, v142
	v_mul_f32_e32 v166, v166, v143
	v_cvt_pk_bf16_f32 v153, v165, v166
	v_lshlrev_b32_e32 v165, 16, v10
	v_and_b32_e32 v166, s28, v10
	v_mul_f32_e32 v165, v165, v144
	v_mul_f32_e32 v166, v166, v145
	v_cvt_pk_bf16_f32 v154, v165, v166
	v_lshlrev_b32_e32 v165, 16, v11
	v_and_b32_e32 v166, s28, v11
	v_mul_f32_e32 v165, v165, v146
	v_mul_f32_e32 v166, v166, v147
	v_cvt_pk_bf16_f32 v155, v165, v166
	s_nop 1
	v_mfma_f32_16x16x32_bf16 v[156:159], v[24:27], v[152:155], v[156:159]
	ds_read_b128 v[140:143], v170 offset:384
	ds_read_b128 v[144:147], v170 offset:400
	s_waitcnt lgkmcnt(2)
	v_lshlrev_b32_e32 v165, 16, v12
	v_and_b32_e32 v166, s28, v12
	v_mul_f32_e32 v165, v165, v132
	v_mul_f32_e32 v166, v166, v133
	v_cvt_pk_bf16_f32 v148, v165, v166
	v_lshlrev_b32_e32 v165, 16, v13
	v_and_b32_e32 v166, s28, v13
	v_mul_f32_e32 v165, v165, v134
	v_mul_f32_e32 v166, v166, v135
	v_cvt_pk_bf16_f32 v149, v165, v166
	v_lshlrev_b32_e32 v165, 16, v14
	v_and_b32_e32 v166, s28, v14
	v_mul_f32_e32 v165, v165, v136
	v_mul_f32_e32 v166, v166, v137
	v_cvt_pk_bf16_f32 v150, v165, v166
	v_lshlrev_b32_e32 v165, 16, v15
	v_and_b32_e32 v166, s28, v15
	v_mul_f32_e32 v165, v165, v138
	v_mul_f32_e32 v166, v166, v139
	v_cvt_pk_bf16_f32 v151, v165, v166
	s_nop 1
	v_mfma_f32_16x16x32_bf16 v[156:159], v[28:31], v[148:151], v[156:159]
	s_waitcnt lgkmcnt(0)
	v_lshlrev_b32_e32 v165, 16, v16
	v_and_b32_e32 v166, s28, v16
	v_mul_f32_e32 v165, v165, v140
	v_mul_f32_e32 v166, v166, v141
	v_cvt_pk_bf16_f32 v152, v165, v166
	v_lshlrev_b32_e32 v165, 16, v17
	v_and_b32_e32 v166, s28, v17
	v_mul_f32_e32 v165, v165, v142
	v_mul_f32_e32 v166, v166, v143
	v_cvt_pk_bf16_f32 v153, v165, v166
	v_lshlrev_b32_e32 v165, 16, v18
	v_and_b32_e32 v166, s28, v18
	v_mul_f32_e32 v165, v165, v144
	v_mul_f32_e32 v166, v166, v145
	v_cvt_pk_bf16_f32 v154, v165, v166
	v_lshlrev_b32_e32 v165, 16, v19
	v_and_b32_e32 v166, s28, v19
	v_mul_f32_e32 v165, v165, v146
	v_mul_f32_e32 v166, v166, v147
	v_cvt_pk_bf16_f32 v155, v165, v166
	s_nop 1
	v_mfma_f32_16x16x32_bf16 v[156:159], v[32:35], v[152:155], v[156:159]
	global_load_dwordx4 v[4:7], v160, s[44:45]
	global_load_dwordx4 v[8:11], v160, s[44:45] offset:64
	global_load_dwordx4 v[12:15], v160, s[44:45] offset:128
	global_load_dwordx4 v[16:19], v160, s[44:45] offset:192
	global_load_dwordx4 v[20:23], v160, s[46:47]
	global_load_dwordx4 v[24:27], v160, s[46:47] offset:64
	global_load_dwordx4 v[28:31], v160, s[46:47] offset:128
	global_load_dwordx4 v[32:35], v160, s[46:47] offset:192
	s_add_u32 s44, s44, s98
	s_addc_u32 s45, s45, s92
	s_add_u32 s46, s46, s99
	s_addc_u32 s47, s47, s92
	s_waitcnt vmcnt(25)
	s_xor_b32 s100, s39, 1
	s_lshl_b32 s100, s100, 9
	v_add_u32_e32 v170, s100, v163
	s_nop 0
	ds_read_b128 v[132:135], v170
	ds_read_b128 v[136:139], v170 offset:16
	v_cvt_pk_bf16_f32 v166, v156, v157
	v_cvt_pk_bf16_f32 v167, v158, v159
	global_store_dwordx2 v162, v[166:167], s[48:49]
	s_nop 0
	s_add_u32 s48, s48, s50
	s_addc_u32 s49, s49, s92
	v_mul_f32_e32 v164, 0x3fb8aa3b, v172
	v_exp_f32_e32 v164, v164
	s_nop 0
	v_mul_f32_e32 v156, v156, v164
	v_mul_f32_e32 v157, v157, v164
	v_mul_f32_e32 v158, v158, v164
	v_mul_f32_e32 v159, v159, v164
	ds_read_b128 v[140:143], v170 offset:128
	ds_read_b128 v[144:147], v170 offset:144
	s_waitcnt lgkmcnt(2)
	v_lshlrev_b32_e32 v165, 16, v36
	v_and_b32_e32 v166, s28, v36
	v_mul_f32_e32 v165, v165, v132
	v_mul_f32_e32 v166, v166, v133
	v_cvt_pk_bf16_f32 v148, v165, v166
	v_lshlrev_b32_e32 v165, 16, v37
	v_and_b32_e32 v166, s28, v37
	v_mul_f32_e32 v165, v165, v134
	v_mul_f32_e32 v166, v166, v135
	v_cvt_pk_bf16_f32 v149, v165, v166
	v_lshlrev_b32_e32 v165, 16, v38
	v_and_b32_e32 v166, s28, v38
	v_mul_f32_e32 v165, v165, v136
	v_mul_f32_e32 v166, v166, v137
	v_cvt_pk_bf16_f32 v150, v165, v166
	v_lshlrev_b32_e32 v165, 16, v39
	v_and_b32_e32 v166, s28, v39
	v_mul_f32_e32 v165, v165, v138
	v_mul_f32_e32 v166, v166, v139
	v_cvt_pk_bf16_f32 v151, v165, v166
	s_nop 1
	v_mfma_f32_16x16x32_bf16 v[156:159], v[52:55], v[148:151], v[156:159]
	ds_read_b128 v[132:135], v170 offset:256
	ds_read_b128 v[136:139], v170 offset:272
	s_waitcnt lgkmcnt(2)
	v_lshlrev_b32_e32 v165, 16, v40
	v_and_b32_e32 v166, s28, v40
	v_mul_f32_e32 v165, v165, v140
	v_mul_f32_e32 v166, v166, v141
	v_cvt_pk_bf16_f32 v152, v165, v166
	v_lshlrev_b32_e32 v165, 16, v41
	v_and_b32_e32 v166, s28, v41
	v_mul_f32_e32 v165, v165, v142
	v_mul_f32_e32 v166, v166, v143
	v_cvt_pk_bf16_f32 v153, v165, v166
	v_lshlrev_b32_e32 v165, 16, v42
	v_and_b32_e32 v166, s28, v42
	v_mul_f32_e32 v165, v165, v144
	v_mul_f32_e32 v166, v166, v145
	v_cvt_pk_bf16_f32 v154, v165, v166
	v_lshlrev_b32_e32 v165, 16, v43
	v_and_b32_e32 v166, s28, v43
	v_mul_f32_e32 v165, v165, v146
	v_mul_f32_e32 v166, v166, v147
	v_cvt_pk_bf16_f32 v155, v165, v166
	s_nop 1
	v_mfma_f32_16x16x32_bf16 v[156:159], v[56:59], v[152:155], v[156:159]
	ds_read_b128 v[140:143], v170 offset:384
	ds_read_b128 v[144:147], v170 offset:400
	s_waitcnt lgkmcnt(2)
	v_lshlrev_b32_e32 v165, 16, v44
	v_and_b32_e32 v166, s28, v44
	v_mul_f32_e32 v165, v165, v132
	v_mul_f32_e32 v166, v166, v133
	v_cvt_pk_bf16_f32 v148, v165, v166
	v_lshlrev_b32_e32 v165, 16, v45
	v_and_b32_e32 v166, s28, v45
	v_mul_f32_e32 v165, v165, v134
	v_mul_f32_e32 v166, v166, v135
	v_cvt_pk_bf16_f32 v149, v165, v166
	v_lshlrev_b32_e32 v165, 16, v46
	v_and_b32_e32 v166, s28, v46
	v_mul_f32_e32 v165, v165, v136
	v_mul_f32_e32 v166, v166, v137
	v_cvt_pk_bf16_f32 v150, v165, v166
	v_lshlrev_b32_e32 v165, 16, v47
	v_and_b32_e32 v166, s28, v47
	v_mul_f32_e32 v165, v165, v138
	v_mul_f32_e32 v166, v166, v139
	v_cvt_pk_bf16_f32 v151, v165, v166
	s_nop 1
	v_mfma_f32_16x16x32_bf16 v[156:159], v[60:63], v[148:151], v[156:159]
	s_waitcnt lgkmcnt(0)
	v_lshlrev_b32_e32 v165, 16, v48
	v_and_b32_e32 v166, s28, v48
	v_mul_f32_e32 v165, v165, v140
	v_mul_f32_e32 v166, v166, v141
	v_cvt_pk_bf16_f32 v152, v165, v166
	v_lshlrev_b32_e32 v165, 16, v49
	v_and_b32_e32 v166, s28, v49
	v_mul_f32_e32 v165, v165, v142
	v_mul_f32_e32 v166, v166, v143
	v_cvt_pk_bf16_f32 v153, v165, v166
	v_lshlrev_b32_e32 v165, 16, v50
	v_and_b32_e32 v166, s28, v50
	v_mul_f32_e32 v165, v165, v144
	v_mul_f32_e32 v166, v166, v145
	v_cvt_pk_bf16_f32 v154, v165, v166
	v_lshlrev_b32_e32 v165, 16, v51
	v_and_b32_e32 v166, s28, v51
	v_mul_f32_e32 v165, v165, v146
	v_mul_f32_e32 v166, v166, v147
	v_cvt_pk_bf16_f32 v155, v165, v166
	s_nop 1
	v_mfma_f32_16x16x32_bf16 v[156:159], v[64:67], v[152:155], v[156:159]
	global_load_dwordx4 v[36:39], v160, s[44:45]
	global_load_dwordx4 v[40:43], v160, s[44:45] offset:64
	global_load_dwordx4 v[44:47], v160, s[44:45] offset:128
	global_load_dwordx4 v[48:51], v160, s[44:45] offset:192
	global_load_dwordx4 v[52:55], v160, s[46:47]
	global_load_dwordx4 v[56:59], v160, s[46:47] offset:64
	global_load_dwordx4 v[60:63], v160, s[46:47] offset:128
	global_load_dwordx4 v[64:67], v160, s[46:47] offset:192
	s_add_u32 s44, s44, s98
	s_addc_u32 s45, s45, s92
	s_add_u32 s46, s46, s99
	s_addc_u32 s47, s47, s92
	s_waitcnt vmcnt(26)
	s_xor_b32 s100, s39, 2
	s_lshl_b32 s100, s100, 9
	v_add_u32_e32 v170, s100, v163
	s_nop 0
	ds_read_b128 v[132:135], v170
	ds_read_b128 v[136:139], v170 offset:16
	v_cvt_pk_bf16_f32 v166, v156, v157
	v_cvt_pk_bf16_f32 v167, v158, v159
	global_store_dwordx2 v162, v[166:167], s[48:49]
	s_nop 0
	s_add_u32 s48, s48, s50
	s_addc_u32 s49, s49, s92
	v_mul_f32_e32 v164, 0x3fb8aa3b, v173
	v_exp_f32_e32 v164, v164
	s_nop 0
	v_mul_f32_e32 v156, v156, v164
	v_mul_f32_e32 v157, v157, v164
	v_mul_f32_e32 v158, v158, v164
	v_mul_f32_e32 v159, v159, v164
	ds_read_b128 v[140:143], v170 offset:128
	ds_read_b128 v[144:147], v170 offset:144
	s_waitcnt lgkmcnt(2)
	v_lshlrev_b32_e32 v165, 16, v68
	v_and_b32_e32 v166, s28, v68
	v_mul_f32_e32 v165, v165, v132
	v_mul_f32_e32 v166, v166, v133
	v_cvt_pk_bf16_f32 v148, v165, v166
	v_lshlrev_b32_e32 v165, 16, v69
	v_and_b32_e32 v166, s28, v69
	v_mul_f32_e32 v165, v165, v134
	v_mul_f32_e32 v166, v166, v135
	v_cvt_pk_bf16_f32 v149, v165, v166
	v_lshlrev_b32_e32 v165, 16, v70
	v_and_b32_e32 v166, s28, v70
	v_mul_f32_e32 v165, v165, v136
	v_mul_f32_e32 v166, v166, v137
	v_cvt_pk_bf16_f32 v150, v165, v166
	v_lshlrev_b32_e32 v165, 16, v71
	v_and_b32_e32 v166, s28, v71
	v_mul_f32_e32 v165, v165, v138
	v_mul_f32_e32 v166, v166, v139
	v_cvt_pk_bf16_f32 v151, v165, v166
	s_nop 1
	v_mfma_f32_16x16x32_bf16 v[156:159], v[84:87], v[148:151], v[156:159]
	ds_read_b128 v[132:135], v170 offset:256
	ds_read_b128 v[136:139], v170 offset:272
	s_waitcnt lgkmcnt(2)
	v_lshlrev_b32_e32 v165, 16, v72
	v_and_b32_e32 v166, s28, v72
	v_mul_f32_e32 v165, v165, v140
	v_mul_f32_e32 v166, v166, v141
	v_cvt_pk_bf16_f32 v152, v165, v166
	v_lshlrev_b32_e32 v165, 16, v73
	v_and_b32_e32 v166, s28, v73
	v_mul_f32_e32 v165, v165, v142
	v_mul_f32_e32 v166, v166, v143
	v_cvt_pk_bf16_f32 v153, v165, v166
	v_lshlrev_b32_e32 v165, 16, v74
	v_and_b32_e32 v166, s28, v74
	v_mul_f32_e32 v165, v165, v144
	v_mul_f32_e32 v166, v166, v145
	v_cvt_pk_bf16_f32 v154, v165, v166
	v_lshlrev_b32_e32 v165, 16, v75
	v_and_b32_e32 v166, s28, v75
	v_mul_f32_e32 v165, v165, v146
	v_mul_f32_e32 v166, v166, v147
	v_cvt_pk_bf16_f32 v155, v165, v166
	s_nop 1
	v_mfma_f32_16x16x32_bf16 v[156:159], v[88:91], v[152:155], v[156:159]
	ds_read_b128 v[140:143], v170 offset:384
	ds_read_b128 v[144:147], v170 offset:400
	s_waitcnt lgkmcnt(2)
	v_lshlrev_b32_e32 v165, 16, v76
	v_and_b32_e32 v166, s28, v76
	v_mul_f32_e32 v165, v165, v132
	v_mul_f32_e32 v166, v166, v133
	v_cvt_pk_bf16_f32 v148, v165, v166
	v_lshlrev_b32_e32 v165, 16, v77
	v_and_b32_e32 v166, s28, v77
	v_mul_f32_e32 v165, v165, v134
	v_mul_f32_e32 v166, v166, v135
	v_cvt_pk_bf16_f32 v149, v165, v166
	v_lshlrev_b32_e32 v165, 16, v78
	v_and_b32_e32 v166, s28, v78
	v_mul_f32_e32 v165, v165, v136
	v_mul_f32_e32 v166, v166, v137
	v_cvt_pk_bf16_f32 v150, v165, v166
	v_lshlrev_b32_e32 v165, 16, v79
	v_and_b32_e32 v166, s28, v79
	v_mul_f32_e32 v165, v165, v138
	v_mul_f32_e32 v166, v166, v139
	v_cvt_pk_bf16_f32 v151, v165, v166
	s_nop 1
	v_mfma_f32_16x16x32_bf16 v[156:159], v[92:95], v[148:151], v[156:159]
	s_waitcnt lgkmcnt(0)
	v_lshlrev_b32_e32 v165, 16, v80
	v_and_b32_e32 v166, s28, v80
	v_mul_f32_e32 v165, v165, v140
	v_mul_f32_e32 v166, v166, v141
	v_cvt_pk_bf16_f32 v152, v165, v166
	v_lshlrev_b32_e32 v165, 16, v81
	v_and_b32_e32 v166, s28, v81
	v_mul_f32_e32 v165, v165, v142
	v_mul_f32_e32 v166, v166, v143
	v_cvt_pk_bf16_f32 v153, v165, v166
	v_lshlrev_b32_e32 v165, 16, v82
	v_and_b32_e32 v166, s28, v82
	v_mul_f32_e32 v165, v165, v144
	v_mul_f32_e32 v166, v166, v145
	v_cvt_pk_bf16_f32 v154, v165, v166
	v_lshlrev_b32_e32 v165, 16, v83
	v_and_b32_e32 v166, s28, v83
	v_mul_f32_e32 v165, v165, v146
	v_mul_f32_e32 v166, v166, v147
	v_cvt_pk_bf16_f32 v155, v165, v166
	s_nop 1
	v_mfma_f32_16x16x32_bf16 v[156:159], v[96:99], v[152:155], v[156:159]
	global_load_dwordx4 v[68:71], v160, s[44:45]
	global_load_dwordx4 v[72:75], v160, s[44:45] offset:64
	global_load_dwordx4 v[76:79], v160, s[44:45] offset:128
	global_load_dwordx4 v[80:83], v160, s[44:45] offset:192
	global_load_dwordx4 v[84:87], v160, s[46:47]
	global_load_dwordx4 v[88:91], v160, s[46:47] offset:64
	global_load_dwordx4 v[92:95], v160, s[46:47] offset:128
	global_load_dwordx4 v[96:99], v160, s[46:47] offset:192
	s_add_u32 s44, s44, s98
	s_addc_u32 s45, s45, s92
	s_add_u32 s46, s46, s99
	s_addc_u32 s47, s47, s92
	s_waitcnt vmcnt(27)
	s_xor_b32 s100, s39, 3
	s_lshl_b32 s100, s100, 9
	v_add_u32_e32 v170, s100, v163
	s_nop 0
	ds_read_b128 v[132:135], v170
	ds_read_b128 v[136:139], v170 offset:16
	v_cvt_pk_bf16_f32 v166, v156, v157
	v_cvt_pk_bf16_f32 v167, v158, v159
	global_store_dwordx2 v162, v[166:167], s[48:49]
	s_nop 0
	s_add_u32 s48, s48, s50
	s_addc_u32 s49, s49, s92
	v_mul_f32_e32 v164, 0x3fb8aa3b, v174
	v_exp_f32_e32 v164, v164
	s_nop 0
	v_mul_f32_e32 v156, v156, v164
	v_mul_f32_e32 v157, v157, v164
	v_mul_f32_e32 v158, v158, v164
	v_mul_f32_e32 v159, v159, v164
	ds_read_b128 v[140:143], v170 offset:128
	ds_read_b128 v[144:147], v170 offset:144
	s_waitcnt lgkmcnt(2)
	v_lshlrev_b32_e32 v165, 16, v100
	v_and_b32_e32 v166, s28, v100
	v_mul_f32_e32 v165, v165, v132
	v_mul_f32_e32 v166, v166, v133
	v_cvt_pk_bf16_f32 v148, v165, v166
	v_lshlrev_b32_e32 v165, 16, v101
	v_and_b32_e32 v166, s28, v101
	v_mul_f32_e32 v165, v165, v134
	v_mul_f32_e32 v166, v166, v135
	v_cvt_pk_bf16_f32 v149, v165, v166
	v_lshlrev_b32_e32 v165, 16, v102
	v_and_b32_e32 v166, s28, v102
	v_mul_f32_e32 v165, v165, v136
	v_mul_f32_e32 v166, v166, v137
	v_cvt_pk_bf16_f32 v150, v165, v166
	v_lshlrev_b32_e32 v165, 16, v103
	v_and_b32_e32 v166, s28, v103
	v_mul_f32_e32 v165, v165, v138
	v_mul_f32_e32 v166, v166, v139
	v_cvt_pk_bf16_f32 v151, v165, v166
	s_nop 1
	v_mfma_f32_16x16x32_bf16 v[156:159], v[116:119], v[148:151], v[156:159]
	ds_read_b128 v[132:135], v170 offset:256
	ds_read_b128 v[136:139], v170 offset:272
	s_waitcnt lgkmcnt(2)
	v_lshlrev_b32_e32 v165, 16, v104
	v_and_b32_e32 v166, s28, v104
	v_mul_f32_e32 v165, v165, v140
	v_mul_f32_e32 v166, v166, v141
	v_cvt_pk_bf16_f32 v152, v165, v166
	v_lshlrev_b32_e32 v165, 16, v105
	v_and_b32_e32 v166, s28, v105
	v_mul_f32_e32 v165, v165, v142
	v_mul_f32_e32 v166, v166, v143
	v_cvt_pk_bf16_f32 v153, v165, v166
	v_lshlrev_b32_e32 v165, 16, v106
	v_and_b32_e32 v166, s28, v106
	v_mul_f32_e32 v165, v165, v144
	v_mul_f32_e32 v166, v166, v145
	v_cvt_pk_bf16_f32 v154, v165, v166
	v_lshlrev_b32_e32 v165, 16, v107
	v_and_b32_e32 v166, s28, v107
	v_mul_f32_e32 v165, v165, v146
	v_mul_f32_e32 v166, v166, v147
	v_cvt_pk_bf16_f32 v155, v165, v166
	s_nop 1
	v_mfma_f32_16x16x32_bf16 v[156:159], v[120:123], v[152:155], v[156:159]
	ds_read_b128 v[140:143], v170 offset:384
	ds_read_b128 v[144:147], v170 offset:400
	s_waitcnt lgkmcnt(2)
	v_lshlrev_b32_e32 v165, 16, v108
	v_and_b32_e32 v166, s28, v108
	v_mul_f32_e32 v165, v165, v132
	v_mul_f32_e32 v166, v166, v133
	v_cvt_pk_bf16_f32 v148, v165, v166
	v_lshlrev_b32_e32 v165, 16, v109
	v_and_b32_e32 v166, s28, v109
	v_mul_f32_e32 v165, v165, v134
	v_mul_f32_e32 v166, v166, v135
	v_cvt_pk_bf16_f32 v149, v165, v166
	v_lshlrev_b32_e32 v165, 16, v110
	v_and_b32_e32 v166, s28, v110
	v_mul_f32_e32 v165, v165, v136
	v_mul_f32_e32 v166, v166, v137
	v_cvt_pk_bf16_f32 v150, v165, v166
	v_lshlrev_b32_e32 v165, 16, v111
	v_and_b32_e32 v166, s28, v111
	v_mul_f32_e32 v165, v165, v138
	v_mul_f32_e32 v166, v166, v139
	v_cvt_pk_bf16_f32 v151, v165, v166
	s_nop 1
	v_mfma_f32_16x16x32_bf16 v[156:159], v[124:127], v[148:151], v[156:159]
	s_waitcnt lgkmcnt(0)
	v_lshlrev_b32_e32 v165, 16, v112
	v_and_b32_e32 v166, s28, v112
	v_mul_f32_e32 v165, v165, v140
	v_mul_f32_e32 v166, v166, v141
	v_cvt_pk_bf16_f32 v152, v165, v166
	v_lshlrev_b32_e32 v165, 16, v113
	v_and_b32_e32 v166, s28, v113
	v_mul_f32_e32 v165, v165, v142
	v_mul_f32_e32 v166, v166, v143
	v_cvt_pk_bf16_f32 v153, v165, v166
	v_lshlrev_b32_e32 v165, 16, v114
	v_and_b32_e32 v166, s28, v114
	v_mul_f32_e32 v165, v165, v144
	v_mul_f32_e32 v166, v166, v145
	v_cvt_pk_bf16_f32 v154, v165, v166
	v_lshlrev_b32_e32 v165, 16, v115
	v_and_b32_e32 v166, s28, v115
	v_mul_f32_e32 v165, v165, v146
	v_mul_f32_e32 v166, v166, v147
	v_cvt_pk_bf16_f32 v155, v165, v166
	s_nop 1
	v_mfma_f32_16x16x32_bf16 v[156:159], v[128:131], v[152:155], v[156:159]
	global_load_dwordx4 v[100:103], v160, s[44:45]
	global_load_dwordx4 v[104:107], v160, s[44:45] offset:64
	global_load_dwordx4 v[108:111], v160, s[44:45] offset:128
	global_load_dwordx4 v[112:115], v160, s[44:45] offset:192
	global_load_dwordx4 v[116:119], v160, s[46:47]
	global_load_dwordx4 v[120:123], v160, s[46:47] offset:64
	global_load_dwordx4 v[124:127], v160, s[46:47] offset:128
	global_load_dwordx4 v[128:131], v160, s[46:47] offset:192
	s_add_u32 s44, s44, s98
	s_addc_u32 s45, s45, s92
	s_add_u32 s46, s46, s99
	s_addc_u32 s47, s47, s92
	s_waitcnt vmcnt(27)
	s_xor_b32 s100, s39, 4
	s_lshl_b32 s100, s100, 9
	v_add_u32_e32 v170, s100, v163
	s_nop 0
	ds_read_b128 v[132:135], v170
	ds_read_b128 v[136:139], v170 offset:16
	v_cvt_pk_bf16_f32 v166, v156, v157
	v_cvt_pk_bf16_f32 v167, v158, v159
	global_store_dwordx2 v162, v[166:167], s[48:49]
	s_nop 0
	s_add_u32 s48, s48, s50
	s_addc_u32 s49, s49, s92
	v_mul_f32_e32 v164, 0x3fb8aa3b, v175
	v_exp_f32_e32 v164, v164
	s_nop 0
	v_mul_f32_e32 v156, v156, v164
	v_mul_f32_e32 v157, v157, v164
	v_mul_f32_e32 v158, v158, v164
	v_mul_f32_e32 v159, v159, v164
	ds_read_b128 v[140:143], v170 offset:128
	ds_read_b128 v[144:147], v170 offset:144
	s_waitcnt lgkmcnt(2)
	v_lshlrev_b32_e32 v165, 16, v4
	v_and_b32_e32 v166, s28, v4
	v_mul_f32_e32 v165, v165, v132
	v_mul_f32_e32 v166, v166, v133
	v_cvt_pk_bf16_f32 v148, v165, v166
	v_lshlrev_b32_e32 v165, 16, v5
	v_and_b32_e32 v166, s28, v5
	v_mul_f32_e32 v165, v165, v134
	v_mul_f32_e32 v166, v166, v135
	v_cvt_pk_bf16_f32 v149, v165, v166
	v_lshlrev_b32_e32 v165, 16, v6
	v_and_b32_e32 v166, s28, v6
	v_mul_f32_e32 v165, v165, v136
	v_mul_f32_e32 v166, v166, v137
	v_cvt_pk_bf16_f32 v150, v165, v166
	v_lshlrev_b32_e32 v165, 16, v7
	v_and_b32_e32 v166, s28, v7
	v_mul_f32_e32 v165, v165, v138
	v_mul_f32_e32 v166, v166, v139
	v_cvt_pk_bf16_f32 v151, v165, v166
	s_nop 1
	v_mfma_f32_16x16x32_bf16 v[156:159], v[20:23], v[148:151], v[156:159]
	ds_read_b128 v[132:135], v170 offset:256
	ds_read_b128 v[136:139], v170 offset:272
	s_waitcnt lgkmcnt(2)
	v_lshlrev_b32_e32 v165, 16, v8
	v_and_b32_e32 v166, s28, v8
	v_mul_f32_e32 v165, v165, v140
	v_mul_f32_e32 v166, v166, v141
	v_cvt_pk_bf16_f32 v152, v165, v166
	v_lshlrev_b32_e32 v165, 16, v9
	v_and_b32_e32 v166, s28, v9
	v_mul_f32_e32 v165, v165, v142
	v_mul_f32_e32 v166, v166, v143
	v_cvt_pk_bf16_f32 v153, v165, v166
	v_lshlrev_b32_e32 v165, 16, v10
	v_and_b32_e32 v166, s28, v10
	v_mul_f32_e32 v165, v165, v144
	v_mul_f32_e32 v166, v166, v145
	v_cvt_pk_bf16_f32 v154, v165, v166
	v_lshlrev_b32_e32 v165, 16, v11
	v_and_b32_e32 v166, s28, v11
	v_mul_f32_e32 v165, v165, v146
	v_mul_f32_e32 v166, v166, v147
	v_cvt_pk_bf16_f32 v155, v165, v166
	s_nop 1
	v_mfma_f32_16x16x32_bf16 v[156:159], v[24:27], v[152:155], v[156:159]
	ds_read_b128 v[140:143], v170 offset:384
	ds_read_b128 v[144:147], v170 offset:400
	s_waitcnt lgkmcnt(2)
	v_lshlrev_b32_e32 v165, 16, v12
	v_and_b32_e32 v166, s28, v12
	v_mul_f32_e32 v165, v165, v132
	v_mul_f32_e32 v166, v166, v133
	v_cvt_pk_bf16_f32 v148, v165, v166
	v_lshlrev_b32_e32 v165, 16, v13
	v_and_b32_e32 v166, s28, v13
	v_mul_f32_e32 v165, v165, v134
	v_mul_f32_e32 v166, v166, v135
	v_cvt_pk_bf16_f32 v149, v165, v166
	v_lshlrev_b32_e32 v165, 16, v14
	v_and_b32_e32 v166, s28, v14
	v_mul_f32_e32 v165, v165, v136
	v_mul_f32_e32 v166, v166, v137
	v_cvt_pk_bf16_f32 v150, v165, v166
	v_lshlrev_b32_e32 v165, 16, v15
	v_and_b32_e32 v166, s28, v15
	v_mul_f32_e32 v165, v165, v138
	v_mul_f32_e32 v166, v166, v139
	v_cvt_pk_bf16_f32 v151, v165, v166
	s_nop 1
	v_mfma_f32_16x16x32_bf16 v[156:159], v[28:31], v[148:151], v[156:159]
	s_waitcnt lgkmcnt(0)
	v_lshlrev_b32_e32 v165, 16, v16
	v_and_b32_e32 v166, s28, v16
	v_mul_f32_e32 v165, v165, v140
	v_mul_f32_e32 v166, v166, v141
	v_cvt_pk_bf16_f32 v152, v165, v166
	v_lshlrev_b32_e32 v165, 16, v17
	v_and_b32_e32 v166, s28, v17
	v_mul_f32_e32 v165, v165, v142
	v_mul_f32_e32 v166, v166, v143
	v_cvt_pk_bf16_f32 v153, v165, v166
	v_lshlrev_b32_e32 v165, 16, v18
	v_and_b32_e32 v166, s28, v18
	v_mul_f32_e32 v165, v165, v144
	v_mul_f32_e32 v166, v166, v145
	v_cvt_pk_bf16_f32 v154, v165, v166
	v_lshlrev_b32_e32 v165, 16, v19
	v_and_b32_e32 v166, s28, v19
	v_mul_f32_e32 v165, v165, v146
	v_mul_f32_e32 v166, v166, v147
	v_cvt_pk_bf16_f32 v155, v165, v166
	s_nop 1
	v_mfma_f32_16x16x32_bf16 v[156:159], v[32:35], v[152:155], v[156:159]
	s_nop 7
	s_waitcnt vmcnt(19)
	s_xor_b32 s100, s39, 5
	s_lshl_b32 s100, s100, 9
	v_add_u32_e32 v170, s100, v163
	s_nop 0
	ds_read_b128 v[132:135], v170
	ds_read_b128 v[136:139], v170 offset:16
	v_cvt_pk_bf16_f32 v166, v156, v157
	v_cvt_pk_bf16_f32 v167, v158, v159
	global_store_dwordx2 v162, v[166:167], s[48:49]
	s_nop 0
	s_add_u32 s48, s48, s50
	s_addc_u32 s49, s49, s92
	v_mul_f32_e32 v164, 0x3fb8aa3b, v176
	v_exp_f32_e32 v164, v164
	s_nop 0
	v_mul_f32_e32 v156, v156, v164
	v_mul_f32_e32 v157, v157, v164
	v_mul_f32_e32 v158, v158, v164
	v_mul_f32_e32 v159, v159, v164
	ds_read_b128 v[140:143], v170 offset:128
	ds_read_b128 v[144:147], v170 offset:144
	s_waitcnt lgkmcnt(2)
	v_lshlrev_b32_e32 v165, 16, v36
	v_and_b32_e32 v166, s28, v36
	v_mul_f32_e32 v165, v165, v132
	v_mul_f32_e32 v166, v166, v133
	v_cvt_pk_bf16_f32 v148, v165, v166
	v_lshlrev_b32_e32 v165, 16, v37
	v_and_b32_e32 v166, s28, v37
	v_mul_f32_e32 v165, v165, v134
	v_mul_f32_e32 v166, v166, v135
	v_cvt_pk_bf16_f32 v149, v165, v166
	v_lshlrev_b32_e32 v165, 16, v38
	v_and_b32_e32 v166, s28, v38
	v_mul_f32_e32 v165, v165, v136
	v_mul_f32_e32 v166, v166, v137
	v_cvt_pk_bf16_f32 v150, v165, v166
	v_lshlrev_b32_e32 v165, 16, v39
	v_and_b32_e32 v166, s28, v39
	v_mul_f32_e32 v165, v165, v138
	v_mul_f32_e32 v166, v166, v139
	v_cvt_pk_bf16_f32 v151, v165, v166
	s_nop 1
	v_mfma_f32_16x16x32_bf16 v[156:159], v[52:55], v[148:151], v[156:159]
	ds_read_b128 v[132:135], v170 offset:256
	ds_read_b128 v[136:139], v170 offset:272
	s_waitcnt lgkmcnt(2)
	v_lshlrev_b32_e32 v165, 16, v40
	v_and_b32_e32 v166, s28, v40
	v_mul_f32_e32 v165, v165, v140
	v_mul_f32_e32 v166, v166, v141
	v_cvt_pk_bf16_f32 v152, v165, v166
	v_lshlrev_b32_e32 v165, 16, v41
	v_and_b32_e32 v166, s28, v41
	v_mul_f32_e32 v165, v165, v142
	v_mul_f32_e32 v166, v166, v143
	v_cvt_pk_bf16_f32 v153, v165, v166
	v_lshlrev_b32_e32 v165, 16, v42
	v_and_b32_e32 v166, s28, v42
	v_mul_f32_e32 v165, v165, v144
	v_mul_f32_e32 v166, v166, v145
	v_cvt_pk_bf16_f32 v154, v165, v166
	v_lshlrev_b32_e32 v165, 16, v43
	v_and_b32_e32 v166, s28, v43
	v_mul_f32_e32 v165, v165, v146
	v_mul_f32_e32 v166, v166, v147
	v_cvt_pk_bf16_f32 v155, v165, v166
	s_nop 1
	v_mfma_f32_16x16x32_bf16 v[156:159], v[56:59], v[152:155], v[156:159]
	ds_read_b128 v[140:143], v170 offset:384
	ds_read_b128 v[144:147], v170 offset:400
	s_waitcnt lgkmcnt(2)
	v_lshlrev_b32_e32 v165, 16, v44
	v_and_b32_e32 v166, s28, v44
	v_mul_f32_e32 v165, v165, v132
	v_mul_f32_e32 v166, v166, v133
	v_cvt_pk_bf16_f32 v148, v165, v166
	v_lshlrev_b32_e32 v165, 16, v45
	v_and_b32_e32 v166, s28, v45
	v_mul_f32_e32 v165, v165, v134
	v_mul_f32_e32 v166, v166, v135
	v_cvt_pk_bf16_f32 v149, v165, v166
	v_lshlrev_b32_e32 v165, 16, v46
	v_and_b32_e32 v166, s28, v46
	v_mul_f32_e32 v165, v165, v136
	v_mul_f32_e32 v166, v166, v137
	v_cvt_pk_bf16_f32 v150, v165, v166
	v_lshlrev_b32_e32 v165, 16, v47
	v_and_b32_e32 v166, s28, v47
	v_mul_f32_e32 v165, v165, v138
	v_mul_f32_e32 v166, v166, v139
	v_cvt_pk_bf16_f32 v151, v165, v166
	s_nop 1
	v_mfma_f32_16x16x32_bf16 v[156:159], v[60:63], v[148:151], v[156:159]
	s_waitcnt lgkmcnt(0)
	v_lshlrev_b32_e32 v165, 16, v48
	v_and_b32_e32 v166, s28, v48
	v_mul_f32_e32 v165, v165, v140
	v_mul_f32_e32 v166, v166, v141
	v_cvt_pk_bf16_f32 v152, v165, v166
	v_lshlrev_b32_e32 v165, 16, v49
	v_and_b32_e32 v166, s28, v49
	v_mul_f32_e32 v165, v165, v142
	v_mul_f32_e32 v166, v166, v143
	v_cvt_pk_bf16_f32 v153, v165, v166
	v_lshlrev_b32_e32 v165, 16, v50
	v_and_b32_e32 v166, s28, v50
	v_mul_f32_e32 v165, v165, v144
	v_mul_f32_e32 v166, v166, v145
	v_cvt_pk_bf16_f32 v154, v165, v166
	v_lshlrev_b32_e32 v165, 16, v51
	v_and_b32_e32 v166, s28, v51
	v_mul_f32_e32 v165, v165, v146
	v_mul_f32_e32 v166, v166, v147
	v_cvt_pk_bf16_f32 v155, v165, v166
	s_nop 1
	v_mfma_f32_16x16x32_bf16 v[156:159], v[64:67], v[152:155], v[156:159]
	s_nop 7
	s_waitcnt vmcnt(11)
	s_xor_b32 s100, s39, 6
	s_lshl_b32 s100, s100, 9
	v_add_u32_e32 v170, s100, v163
	s_nop 0
	ds_read_b128 v[132:135], v170
	ds_read_b128 v[136:139], v170 offset:16
	v_cvt_pk_bf16_f32 v166, v156, v157
	v_cvt_pk_bf16_f32 v167, v158, v159
	global_store_dwordx2 v162, v[166:167], s[48:49]
	s_nop 0
	s_add_u32 s48, s48, s50
	s_addc_u32 s49, s49, s92
	v_mul_f32_e32 v164, 0x3fb8aa3b, v177
	v_exp_f32_e32 v164, v164
	s_nop 0
	v_mul_f32_e32 v156, v156, v164
	v_mul_f32_e32 v157, v157, v164
	v_mul_f32_e32 v158, v158, v164
	v_mul_f32_e32 v159, v159, v164
	ds_read_b128 v[140:143], v170 offset:128
	ds_read_b128 v[144:147], v170 offset:144
	s_waitcnt lgkmcnt(2)
	v_lshlrev_b32_e32 v165, 16, v68
	v_and_b32_e32 v166, s28, v68
	v_mul_f32_e32 v165, v165, v132
	v_mul_f32_e32 v166, v166, v133
	v_cvt_pk_bf16_f32 v148, v165, v166
	v_lshlrev_b32_e32 v165, 16, v69
	v_and_b32_e32 v166, s28, v69
	v_mul_f32_e32 v165, v165, v134
	v_mul_f32_e32 v166, v166, v135
	v_cvt_pk_bf16_f32 v149, v165, v166
	v_lshlrev_b32_e32 v165, 16, v70
	v_and_b32_e32 v166, s28, v70
	v_mul_f32_e32 v165, v165, v136
	v_mul_f32_e32 v166, v166, v137
	v_cvt_pk_bf16_f32 v150, v165, v166
	v_lshlrev_b32_e32 v165, 16, v71
	v_and_b32_e32 v166, s28, v71
	v_mul_f32_e32 v165, v165, v138
	v_mul_f32_e32 v166, v166, v139
	v_cvt_pk_bf16_f32 v151, v165, v166
	s_nop 1
	v_mfma_f32_16x16x32_bf16 v[156:159], v[84:87], v[148:151], v[156:159]
	ds_read_b128 v[132:135], v170 offset:256
	ds_read_b128 v[136:139], v170 offset:272
	s_waitcnt lgkmcnt(2)
	v_lshlrev_b32_e32 v165, 16, v72
	v_and_b32_e32 v166, s28, v72
	v_mul_f32_e32 v165, v165, v140
	v_mul_f32_e32 v166, v166, v141
	v_cvt_pk_bf16_f32 v152, v165, v166
	v_lshlrev_b32_e32 v165, 16, v73
	v_and_b32_e32 v166, s28, v73
	v_mul_f32_e32 v165, v165, v142
	v_mul_f32_e32 v166, v166, v143
	v_cvt_pk_bf16_f32 v153, v165, v166
	v_lshlrev_b32_e32 v165, 16, v74
	v_and_b32_e32 v166, s28, v74
	v_mul_f32_e32 v165, v165, v144
	v_mul_f32_e32 v166, v166, v145
	v_cvt_pk_bf16_f32 v154, v165, v166
	v_lshlrev_b32_e32 v165, 16, v75
	v_and_b32_e32 v166, s28, v75
	v_mul_f32_e32 v165, v165, v146
	v_mul_f32_e32 v166, v166, v147
	v_cvt_pk_bf16_f32 v155, v165, v166
	s_nop 1
	v_mfma_f32_16x16x32_bf16 v[156:159], v[88:91], v[152:155], v[156:159]
	ds_read_b128 v[140:143], v170 offset:384
	ds_read_b128 v[144:147], v170 offset:400
	s_waitcnt lgkmcnt(2)
	v_lshlrev_b32_e32 v165, 16, v76
	v_and_b32_e32 v166, s28, v76
	v_mul_f32_e32 v165, v165, v132
	v_mul_f32_e32 v166, v166, v133
	v_cvt_pk_bf16_f32 v148, v165, v166
	v_lshlrev_b32_e32 v165, 16, v77
	v_and_b32_e32 v166, s28, v77
	v_mul_f32_e32 v165, v165, v134
	v_mul_f32_e32 v166, v166, v135
	v_cvt_pk_bf16_f32 v149, v165, v166
	v_lshlrev_b32_e32 v165, 16, v78
	v_and_b32_e32 v166, s28, v78
	v_mul_f32_e32 v165, v165, v136
	v_mul_f32_e32 v166, v166, v137
	v_cvt_pk_bf16_f32 v150, v165, v166
	v_lshlrev_b32_e32 v165, 16, v79
	v_and_b32_e32 v166, s28, v79
	v_mul_f32_e32 v165, v165, v138
	v_mul_f32_e32 v166, v166, v139
	v_cvt_pk_bf16_f32 v151, v165, v166
	s_nop 1
	v_mfma_f32_16x16x32_bf16 v[156:159], v[92:95], v[148:151], v[156:159]
	s_waitcnt lgkmcnt(0)
	v_lshlrev_b32_e32 v165, 16, v80
	v_and_b32_e32 v166, s28, v80
	v_mul_f32_e32 v165, v165, v140
	v_mul_f32_e32 v166, v166, v141
	v_cvt_pk_bf16_f32 v152, v165, v166
	v_lshlrev_b32_e32 v165, 16, v81
	v_and_b32_e32 v166, s28, v81
	v_mul_f32_e32 v165, v165, v142
	v_mul_f32_e32 v166, v166, v143
	v_cvt_pk_bf16_f32 v153, v165, v166
	v_lshlrev_b32_e32 v165, 16, v82
	v_and_b32_e32 v166, s28, v82
	v_mul_f32_e32 v165, v165, v144
	v_mul_f32_e32 v166, v166, v145
	v_cvt_pk_bf16_f32 v154, v165, v166
	v_lshlrev_b32_e32 v165, 16, v83
	v_and_b32_e32 v166, s28, v83
	v_mul_f32_e32 v165, v165, v146
	v_mul_f32_e32 v166, v166, v147
	v_cvt_pk_bf16_f32 v155, v165, v166
	s_nop 1
	v_mfma_f32_16x16x32_bf16 v[156:159], v[96:99], v[152:155], v[156:159]
	s_nop 7
	s_waitcnt vmcnt(3)
	s_xor_b32 s100, s39, 7
	s_lshl_b32 s100, s100, 9
	v_add_u32_e32 v170, s100, v163
	s_nop 0
	ds_read_b128 v[132:135], v170
	ds_read_b128 v[136:139], v170 offset:16
	v_cvt_pk_bf16_f32 v166, v156, v157
	v_cvt_pk_bf16_f32 v167, v158, v159
	global_store_dwordx2 v162, v[166:167], s[48:49]
	s_nop 0
	s_add_u32 s48, s48, s50
	s_addc_u32 s49, s49, s92
	v_mul_f32_e32 v164, 0x3fb8aa3b, v178
	v_exp_f32_e32 v164, v164
	s_nop 0
	v_mul_f32_e32 v156, v156, v164
	v_mul_f32_e32 v157, v157, v164
	v_mul_f32_e32 v158, v158, v164
	v_mul_f32_e32 v159, v159, v164
	ds_read_b128 v[140:143], v170 offset:128
	ds_read_b128 v[144:147], v170 offset:144
	s_waitcnt lgkmcnt(2)
	v_lshlrev_b32_e32 v165, 16, v100
	v_and_b32_e32 v166, s28, v100
	v_mul_f32_e32 v165, v165, v132
	v_mul_f32_e32 v166, v166, v133
	v_cvt_pk_bf16_f32 v148, v165, v166
	v_lshlrev_b32_e32 v165, 16, v101
	v_and_b32_e32 v166, s28, v101
	v_mul_f32_e32 v165, v165, v134
	v_mul_f32_e32 v166, v166, v135
	v_cvt_pk_bf16_f32 v149, v165, v166
	v_lshlrev_b32_e32 v165, 16, v102
	v_and_b32_e32 v166, s28, v102
	v_mul_f32_e32 v165, v165, v136
	v_mul_f32_e32 v166, v166, v137
	v_cvt_pk_bf16_f32 v150, v165, v166
	v_lshlrev_b32_e32 v165, 16, v103
	v_and_b32_e32 v166, s28, v103
	v_mul_f32_e32 v165, v165, v138
	v_mul_f32_e32 v166, v166, v139
	v_cvt_pk_bf16_f32 v151, v165, v166
	s_nop 1
	v_mfma_f32_16x16x32_bf16 v[156:159], v[116:119], v[148:151], v[156:159]
	ds_read_b128 v[132:135], v170 offset:256
	ds_read_b128 v[136:139], v170 offset:272
	s_waitcnt lgkmcnt(2)
	v_lshlrev_b32_e32 v165, 16, v104
	v_and_b32_e32 v166, s28, v104
	v_mul_f32_e32 v165, v165, v140
	v_mul_f32_e32 v166, v166, v141
	v_cvt_pk_bf16_f32 v152, v165, v166
	v_lshlrev_b32_e32 v165, 16, v105
	v_and_b32_e32 v166, s28, v105
	v_mul_f32_e32 v165, v165, v142
	v_mul_f32_e32 v166, v166, v143
	v_cvt_pk_bf16_f32 v153, v165, v166
	v_lshlrev_b32_e32 v165, 16, v106
	v_and_b32_e32 v166, s28, v106
	v_mul_f32_e32 v165, v165, v144
	v_mul_f32_e32 v166, v166, v145
	v_cvt_pk_bf16_f32 v154, v165, v166
	v_lshlrev_b32_e32 v165, 16, v107
	v_and_b32_e32 v166, s28, v107
	v_mul_f32_e32 v165, v165, v146
	v_mul_f32_e32 v166, v166, v147
	v_cvt_pk_bf16_f32 v155, v165, v166
	s_nop 1
	v_mfma_f32_16x16x32_bf16 v[156:159], v[120:123], v[152:155], v[156:159]
	ds_read_b128 v[140:143], v170 offset:384
	ds_read_b128 v[144:147], v170 offset:400
	s_waitcnt lgkmcnt(2)
	v_lshlrev_b32_e32 v165, 16, v108
	v_and_b32_e32 v166, s28, v108
	v_mul_f32_e32 v165, v165, v132
	v_mul_f32_e32 v166, v166, v133
	v_cvt_pk_bf16_f32 v148, v165, v166
	v_lshlrev_b32_e32 v165, 16, v109
	v_and_b32_e32 v166, s28, v109
	v_mul_f32_e32 v165, v165, v134
	v_mul_f32_e32 v166, v166, v135
	v_cvt_pk_bf16_f32 v149, v165, v166
	v_lshlrev_b32_e32 v165, 16, v110
	v_and_b32_e32 v166, s28, v110
	v_mul_f32_e32 v165, v165, v136
	v_mul_f32_e32 v166, v166, v137
	v_cvt_pk_bf16_f32 v150, v165, v166
	v_lshlrev_b32_e32 v165, 16, v111
	v_and_b32_e32 v166, s28, v111
	v_mul_f32_e32 v165, v165, v138
	v_mul_f32_e32 v166, v166, v139
	v_cvt_pk_bf16_f32 v151, v165, v166
	s_nop 1
	v_mfma_f32_16x16x32_bf16 v[156:159], v[124:127], v[148:151], v[156:159]
	s_waitcnt lgkmcnt(0)
	v_lshlrev_b32_e32 v165, 16, v112
	v_and_b32_e32 v166, s28, v112
	v_mul_f32_e32 v165, v165, v140
	v_mul_f32_e32 v166, v166, v141
	v_cvt_pk_bf16_f32 v152, v165, v166
	v_lshlrev_b32_e32 v165, 16, v113
	v_and_b32_e32 v166, s28, v113
	v_mul_f32_e32 v165, v165, v142
	v_mul_f32_e32 v166, v166, v143
	v_cvt_pk_bf16_f32 v153, v165, v166
	v_lshlrev_b32_e32 v165, 16, v114
	v_and_b32_e32 v166, s28, v114
	v_mul_f32_e32 v165, v165, v144
	v_mul_f32_e32 v166, v166, v145
	v_cvt_pk_bf16_f32 v154, v165, v166
	v_lshlrev_b32_e32 v165, 16, v115
	v_and_b32_e32 v166, s28, v115
	v_mul_f32_e32 v165, v165, v146
	v_mul_f32_e32 v166, v166, v147
	v_cvt_pk_bf16_f32 v155, v165, v166
	s_nop 1
	v_mfma_f32_16x16x32_bf16 v[156:159], v[128:131], v[152:155], v[156:159]
	s_nop 7
	s_branch .Lsp3_s5o

.Lsp3_cctx:
	s_add_u32 s35, s63, 0x80
	v_lshrrev_b32_e32 v0, 6, v206
	s_nop 0
	v_readfirstlane_b32 s40, v0
	s_lshr_b32 s43, s40, 2
	s_lshl_b32 s43, s43, 2
	v_and_b32_e32 v228, 63, v206
	v_lshrrev_b32_e32 v229, 6, v206
	v_and_b32_e32 v0, 15, v228
	v_readfirstlane_b32 s40, v229
	v_lshrrev_b32_e32 v1, 4, v228
	s_sub_u32 s38, s35, 0x80
	s_and_b32 s42, s40, 3
	s_lshr_b32 s100, s38, 4
	s_lshl_b32 s101, s100, 1
	s_bfe_u32 s41, s38, 0x30001
	s_and_b32 s39, s38, 1
	s_lshl_b32 s52, s100, 1
	s_add_u32 s52, s52, s36
	s_lshl_b32 s52, s52, 1
	s_add_u32 s52, s52, s39
	s_lshl_b32 s52, s52, 3
	s_add_u32 s52, s52, s41
	s_add_u32 s100, s101, 1
	s_cmp_eq_u32 s39, 0
	s_cselect_b32 s101, s101, s100
	s_cselect_b32 s92, 0, -1
	s_mov_b32 s98, 0xfffe0000
	s_cselect_b32 s98, 0x20000, s98
	s_mov_b32 s99, 0xffff0000
	s_cselect_b32 s99, 0x10000, s99
	s_mov_b32 s50, 0xfffc0000
	s_cselect_b32 s50, 0x40000, s50
	s_mov_b32 s51, 0xffffe000
	s_cselect_b32 s51, 0x2000, s51
	s_lshl_b32 s100, s101, 3
	s_add_u32 s100, s100, s41
	s_lshl_b32 s100, s100, 14
	s_lshl_b32 s53, s42, 12
	s_add_u32 s100, s100, s53
	s_add_u32 s100, s100, 0xc184000
	s_add_u32 s44, s96, s100
	s_addc_u32 s45, s97, 0
	s_lshl_b32 s100, s101, 1
	s_lshr_b32 s53, s41, 2
	s_add_u32 s100, s100, s53
	s_lshl_b32 s100, s100, 15
	s_lshl_b32 s53, s43, 12
	s_add_u32 s100, s100, s53
	s_add_u32 s100, s100, 0xbe84000
	s_add_u32 s46, s96, s100
	s_addc_u32 s47, s97, 0
	s_lshl_b32 s100, s101, 1
	s_add_u32 s100, s100, s39
	s_lshl_b32 s100, s100, 3
	s_add_u32 s100, s100, s41
	s_lshl_b32 s53, s100, 14
	s_lshl_b32 s59, s42, 12
	s_add_u32 s53, s53, s59
	s_lshl_b32 s59, s43, 5
	s_add_u32 s53, s53, s59
	s_add_u32 s53, s53, 0xac84000
	s_add_u32 s48, s96, s53
	s_addc_u32 s49, s97, 0
	s_lshl_b32 s100, s100, 9
	s_add_u32 s53, s100, 0xcae4000
	s_add_u32 s58, s96, s53
	s_addc_u32 s59, s97, 0
	s_cmp_eq_u32 s39, 0
	s_cselect_b32 s53, 0x1fc, 0
	s_add_u32 s58, s58, s53
	s_addc_u32 s59, s59, 0
	global_load_dword v227, v2, s[58:59]
	s_add_u32 s58, s58, s51
	s_addc_u32 s59, s59, s92
	global_load_dword v232, v2, s[58:59]
	s_add_u32 s53, s100, 0xcb44000
	s_add_u32 s58, s96, s53
	s_addc_u32 s59, s97, 0
	s_cmp_eq_u32 s39, 0
	s_cbranch_scc1 .Lch_sctx_fw
	s_sub_u32 s58, s58, 0x2000
	s_subb_u32 s59, s59, 0
.Lch_sctx_fw:
	v_lshrrev_b32_e32 v230, 5, v228
	v_and_b32_e32 v231, 31, v228
	v_lshlrev_b32_e32 v230, 13, v230
	v_lshl_add_u32 v230, v231, 4, v230
	s_mul_i32 s53, s40, 16896
	s_lshl_b32 s100, s51, 1
	s_add_u32 m0, s53, 0x0
	s_nop 0
	global_load_lds_dwordx4 v230, s[58:59]
	v_lshlrev_b32_e32 v3, 8, v0
	v_lshl_add_u32 v3, v1, 4, v3
	v_add_u32_e32 v197, 0x1000, v3
	v_add_u32_e32 v199, 0x2000, v3
	v_add_u32_e32 v204, 0x3000, v3
	v_lshlrev_b32_e32 v205, 9, v0
	v_lshl_add_u32 v205, v1, 4, v205
	v_lshrrev_b32_e32 v221, 1, v205
	v_lshl_add_u32 v226, v1, 5, s53
	v_mov_b32_e32 v188, 0
	v_mov_b32_e32 v189, 0
	v_mov_b32_e32 v190, 0
	v_mov_b32_e32 v191, 0
	v_mov_b32_e32 v192, 0
	v_mov_b32_e32 v193, 0
	v_mov_b32_e32 v194, 0
	v_mov_b32_e32 v195, 0
	v_mov_b32_e32 v200, 0
	v_mov_b32_e32 v201, 0
	v_mov_b32_e32 v202, 0
	v_mov_b32_e32 v203, 0
	v_mov_b32_e32 v222, 0
	v_mov_b32_e32 v223, 0
	v_mov_b32_e32 v224, 0
	v_mov_b32_e32 v225, 0
	global_load_dwordx4 v[4:7], v3, s[44:45]
	global_load_dwordx4 v[8:11], v3, s[44:45] offset:64
	global_load_dwordx4 v[12:15], v3, s[44:45] offset:128
	global_load_dwordx4 v[16:19], v3, s[44:45] offset:192
	global_load_dwordx4 v[20:23], v3, s[46:47]
	global_load_dwordx4 v[24:27], v197, s[46:47]
	global_load_dwordx4 v[28:31], v199, s[46:47]
	global_load_dwordx4 v[32:35], v204, s[46:47]
	global_load_dwordx4 v[36:39], v3, s[46:47] offset:64
	global_load_dwordx4 v[40:43], v197, s[46:47] offset:64
	global_load_dwordx4 v[44:47], v199, s[46:47] offset:64
	global_load_dwordx4 v[48:51], v204, s[46:47] offset:64
	global_load_dwordx4 v[52:55], v3, s[46:47] offset:128
	global_load_dwordx4 v[56:59], v197, s[46:47] offset:128
	global_load_dwordx4 v[60:63], v199, s[46:47] offset:128
	global_load_dwordx4 v[64:67], v204, s[46:47] offset:128
	global_load_dwordx4 v[68:71], v3, s[46:47] offset:192
	global_load_dwordx4 v[72:75], v197, s[46:47] offset:192
	global_load_dwordx4 v[76:79], v199, s[46:47] offset:192
	global_load_dwordx4 v[80:83], v204, s[46:47] offset:192
	s_add_u32 s44, s44, s98
	s_addc_u32 s45, s45, s92
	s_add_u32 s46, s46, s99
	s_addc_u32 s47, s47, s92
	global_load_dwordx4 v[84:87], v3, s[44:45]
	global_load_dwordx4 v[88:91], v3, s[44:45] offset:64
	global_load_dwordx4 v[92:95], v3, s[44:45] offset:128
	global_load_dwordx4 v[96:99], v3, s[44:45] offset:192
	global_load_dwordx4 v[100:103], v3, s[46:47]
	global_load_dwordx4 v[104:107], v197, s[46:47]
	global_load_dwordx4 v[108:111], v199, s[46:47]
	global_load_dwordx4 v[112:115], v204, s[46:47]
	global_load_dwordx4 v[116:119], v3, s[46:47] offset:64
	global_load_dwordx4 v[120:123], v197, s[46:47] offset:64
	global_load_dwordx4 v[124:127], v199, s[46:47] offset:64
	global_load_dwordx4 v[128:131], v204, s[46:47] offset:64
	global_load_dwordx4 v[132:135], v3, s[46:47] offset:128
	global_load_dwordx4 v[136:139], v197, s[46:47] offset:128
	global_load_dwordx4 v[140:143], v199, s[46:47] offset:128
	global_load_dwordx4 v[144:147], v204, s[46:47] offset:128
	global_load_dwordx4 v[148:151], v3, s[46:47] offset:192
	global_load_dwordx4 v[152:155], v197, s[46:47] offset:192
	global_load_dwordx4 v[156:159], v199, s[46:47] offset:192
	global_load_dwordx4 v[160:163], v204, s[46:47] offset:192
	s_add_u32 s44, s44, s98
	s_addc_u32 s45, s45, s92
	s_add_u32 s46, s46, s99
	s_addc_u32 s47, s47, s92
	s_waitcnt vmcnt(20)
	s_xor_b32 s100, s39, 0
	s_lshl_b32 s100, s100, 9
	v_add_u32_e32 v233, s100, v226
	s_nop 0
	ds_read_b128 v[164:167], v233
	ds_read_b128 v[168:171], v233 offset:16
	v_cvt_pk_bf16_f32 v228, v188, v189
	v_cvt_pk_bf16_f32 v229, v190, v191
	global_store_dwordx2 v221, v[228:229], s[48:49]
	s_nop 0
	v_cvt_pk_bf16_f32 v228, v192, v193
	v_cvt_pk_bf16_f32 v229, v194, v195
	global_store_dwordx2 v221, v[228:229], s[48:49] offset:32
	s_nop 0
	v_cvt_pk_bf16_f32 v228, v200, v201
	v_cvt_pk_bf16_f32 v229, v202, v203
	global_store_dwordx2 v221, v[228:229], s[48:49] offset:64
	s_nop 0
	v_cvt_pk_bf16_f32 v228, v222, v223
	v_cvt_pk_bf16_f32 v229, v224, v225
	global_store_dwordx2 v221, v[228:229], s[48:49] offset:96
	s_nop 0
	s_add_u32 s48, s48, s50
	s_addc_u32 s49, s49, s92
	v_mul_f32_e32 v227, 0x3fb8aa3b, v227
	v_exp_f32_e32 v227, v227
	s_nop 0
	v_mul_f32_e32 v188, v188, v227
	v_mul_f32_e32 v189, v189, v227
	v_mul_f32_e32 v190, v190, v227
	v_mul_f32_e32 v191, v191, v227
	v_mul_f32_e32 v192, v192, v227
	v_mul_f32_e32 v193, v193, v227
	v_mul_f32_e32 v194, v194, v227
	v_mul_f32_e32 v195, v195, v227
	v_mul_f32_e32 v200, v200, v227
	v_mul_f32_e32 v201, v201, v227
	v_mul_f32_e32 v202, v202, v227
	v_mul_f32_e32 v203, v203, v227
	v_mul_f32_e32 v222, v222, v227
	v_mul_f32_e32 v223, v223, v227
	v_mul_f32_e32 v224, v224, v227
	v_mul_f32_e32 v225, v225, v227
	ds_read_b128 v[172:175], v233 offset:128
	ds_read_b128 v[176:179], v233 offset:144
	s_waitcnt lgkmcnt(2)
	v_lshlrev_b32_e32 v228, 16, v4
	v_and_b32_e32 v229, s28, v4
	v_mul_f32_e32 v228, v228, v164
	v_mul_f32_e32 v229, v229, v165
	v_cvt_pk_bf16_f32 v180, v228, v229
	v_lshlrev_b32_e32 v228, 16, v5
	v_and_b32_e32 v229, s28, v5
	v_mul_f32_e32 v228, v228, v166
	v_mul_f32_e32 v229, v229, v167
	v_cvt_pk_bf16_f32 v181, v228, v229
	v_lshlrev_b32_e32 v228, 16, v6
	v_and_b32_e32 v229, s28, v6
	v_mul_f32_e32 v228, v228, v168
	v_mul_f32_e32 v229, v229, v169
	v_cvt_pk_bf16_f32 v182, v228, v229
	v_lshlrev_b32_e32 v228, 16, v7
	v_and_b32_e32 v229, s28, v7
	v_mul_f32_e32 v228, v228, v170
	v_mul_f32_e32 v229, v229, v171
	v_cvt_pk_bf16_f32 v183, v228, v229
	s_nop 1
	v_mfma_f32_16x16x32_bf16 v[188:191], v[20:23], v[180:183], v[188:191]
	v_mfma_f32_16x16x32_bf16 v[192:195], v[24:27], v[180:183], v[192:195]
	v_mfma_f32_16x16x32_bf16 v[200:203], v[28:31], v[180:183], v[200:203]
	v_mfma_f32_16x16x32_bf16 v[222:225], v[32:35], v[180:183], v[222:225]
	ds_read_b128 v[164:167], v233 offset:256
	ds_read_b128 v[168:171], v233 offset:272
	s_waitcnt lgkmcnt(2)
	v_lshlrev_b32_e32 v228, 16, v8
	v_and_b32_e32 v229, s28, v8
	v_mul_f32_e32 v228, v228, v172
	v_mul_f32_e32 v229, v229, v173
	v_cvt_pk_bf16_f32 v184, v228, v229
	v_lshlrev_b32_e32 v228, 16, v9
	v_and_b32_e32 v229, s28, v9
	v_mul_f32_e32 v228, v228, v174
	v_mul_f32_e32 v229, v229, v175
	v_cvt_pk_bf16_f32 v185, v228, v229
	v_lshlrev_b32_e32 v228, 16, v10
	v_and_b32_e32 v229, s28, v10
	v_mul_f32_e32 v228, v228, v176
	v_mul_f32_e32 v229, v229, v177
	v_cvt_pk_bf16_f32 v186, v228, v229
	v_lshlrev_b32_e32 v228, 16, v11
	v_and_b32_e32 v229, s28, v11
	v_mul_f32_e32 v228, v228, v178
	v_mul_f32_e32 v229, v229, v179
	v_cvt_pk_bf16_f32 v187, v228, v229
	s_nop 1
	v_mfma_f32_16x16x32_bf16 v[188:191], v[36:39], v[184:187], v[188:191]
	v_mfma_f32_16x16x32_bf16 v[192:195], v[40:43], v[184:187], v[192:195]
	v_mfma_f32_16x16x32_bf16 v[200:203], v[44:47], v[184:187], v[200:203]
	v_mfma_f32_16x16x32_bf16 v[222:225], v[48:51], v[184:187], v[222:225]
	ds_read_b128 v[172:175], v233 offset:384
	ds_read_b128 v[176:179], v233 offset:400
	s_waitcnt lgkmcnt(2)
	v_lshlrev_b32_e32 v228, 16, v12
	v_and_b32_e32 v229, s28, v12
	v_mul_f32_e32 v228, v228, v164
	v_mul_f32_e32 v229, v229, v165
	v_cvt_pk_bf16_f32 v180, v228, v229
	v_lshlrev_b32_e32 v228, 16, v13
	v_and_b32_e32 v229, s28, v13
	v_mul_f32_e32 v228, v228, v166
	v_mul_f32_e32 v229, v229, v167
	v_cvt_pk_bf16_f32 v181, v228, v229
	v_lshlrev_b32_e32 v228, 16, v14
	v_and_b32_e32 v229, s28, v14
	v_mul_f32_e32 v228, v228, v168
	v_mul_f32_e32 v229, v229, v169
	v_cvt_pk_bf16_f32 v182, v228, v229
	v_lshlrev_b32_e32 v228, 16, v15
	v_and_b32_e32 v229, s28, v15
	v_mul_f32_e32 v228, v228, v170
	v_mul_f32_e32 v229, v229, v171
	v_cvt_pk_bf16_f32 v183, v228, v229
	s_nop 1
	v_mfma_f32_16x16x32_bf16 v[188:191], v[52:55], v[180:183], v[188:191]
	v_mfma_f32_16x16x32_bf16 v[192:195], v[56:59], v[180:183], v[192:195]
	v_mfma_f32_16x16x32_bf16 v[200:203], v[60:63], v[180:183], v[200:203]
	v_mfma_f32_16x16x32_bf16 v[222:225], v[64:67], v[180:183], v[222:225]
	s_waitcnt lgkmcnt(0)
	v_lshlrev_b32_e32 v228, 16, v16
	v_and_b32_e32 v229, s28, v16
	v_mul_f32_e32 v228, v228, v172
	v_mul_f32_e32 v229, v229, v173
	v_cvt_pk_bf16_f32 v184, v228, v229
	v_lshlrev_b32_e32 v228, 16, v17
	v_and_b32_e32 v229, s28, v17
	v_mul_f32_e32 v228, v228, v174
	v_mul_f32_e32 v229, v229, v175
	v_cvt_pk_bf16_f32 v185, v228, v229
	v_lshlrev_b32_e32 v228, 16, v18
	v_and_b32_e32 v229, s28, v18
	v_mul_f32_e32 v228, v228, v176
	v_mul_f32_e32 v229, v229, v177
	v_cvt_pk_bf16_f32 v186, v228, v229
	v_lshlrev_b32_e32 v228, 16, v19
	v_and_b32_e32 v229, s28, v19
	v_mul_f32_e32 v228, v228, v178
	v_mul_f32_e32 v229, v229, v179
	v_cvt_pk_bf16_f32 v187, v228, v229
	s_nop 1
	v_mfma_f32_16x16x32_bf16 v[188:191], v[68:71], v[184:187], v[188:191]
	v_mfma_f32_16x16x32_bf16 v[192:195], v[72:75], v[184:187], v[192:195]
	v_mfma_f32_16x16x32_bf16 v[200:203], v[76:79], v[184:187], v[200:203]
	v_mfma_f32_16x16x32_bf16 v[222:225], v[80:83], v[184:187], v[222:225]
	s_nop 7
	s_waitcnt vmcnt(4)
	s_xor_b32 s100, s39, 1
	s_lshl_b32 s100, s100, 9
	v_add_u32_e32 v233, s100, v226
	s_nop 0
	ds_read_b128 v[164:167], v233
	ds_read_b128 v[168:171], v233 offset:16
	v_cvt_pk_bf16_f32 v228, v188, v189
	v_cvt_pk_bf16_f32 v229, v190, v191
	global_store_dwordx2 v221, v[228:229], s[48:49]
	s_nop 0
	v_cvt_pk_bf16_f32 v228, v192, v193
	v_cvt_pk_bf16_f32 v229, v194, v195
	global_store_dwordx2 v221, v[228:229], s[48:49] offset:32
	s_nop 0
	v_cvt_pk_bf16_f32 v228, v200, v201
	v_cvt_pk_bf16_f32 v229, v202, v203
	global_store_dwordx2 v221, v[228:229], s[48:49] offset:64
	s_nop 0
	v_cvt_pk_bf16_f32 v228, v222, v223
	v_cvt_pk_bf16_f32 v229, v224, v225
	global_store_dwordx2 v221, v[228:229], s[48:49] offset:96
	s_nop 0
	s_add_u32 s48, s48, s50
	s_addc_u32 s49, s49, s92
	v_mul_f32_e32 v227, 0x3fb8aa3b, v232
	v_exp_f32_e32 v227, v227
	s_nop 0
	v_mul_f32_e32 v188, v188, v227
	v_mul_f32_e32 v189, v189, v227
	v_mul_f32_e32 v190, v190, v227
	v_mul_f32_e32 v191, v191, v227
	v_mul_f32_e32 v192, v192, v227
	v_mul_f32_e32 v193, v193, v227
	v_mul_f32_e32 v194, v194, v227
	v_mul_f32_e32 v195, v195, v227
	v_mul_f32_e32 v200, v200, v227
	v_mul_f32_e32 v201, v201, v227
	v_mul_f32_e32 v202, v202, v227
	v_mul_f32_e32 v203, v203, v227
	v_mul_f32_e32 v222, v222, v227
	v_mul_f32_e32 v223, v223, v227
	v_mul_f32_e32 v224, v224, v227
	v_mul_f32_e32 v225, v225, v227
	ds_read_b128 v[172:175], v233 offset:128
	ds_read_b128 v[176:179], v233 offset:144
	s_waitcnt lgkmcnt(2)
	v_lshlrev_b32_e32 v228, 16, v84
	v_and_b32_e32 v229, s28, v84
	v_mul_f32_e32 v228, v228, v164
	v_mul_f32_e32 v229, v229, v165
	v_cvt_pk_bf16_f32 v180, v228, v229
	v_lshlrev_b32_e32 v228, 16, v85
	v_and_b32_e32 v229, s28, v85
	v_mul_f32_e32 v228, v228, v166
	v_mul_f32_e32 v229, v229, v167
	v_cvt_pk_bf16_f32 v181, v228, v229
	v_lshlrev_b32_e32 v228, 16, v86
	v_and_b32_e32 v229, s28, v86
	v_mul_f32_e32 v228, v228, v168
	v_mul_f32_e32 v229, v229, v169
	v_cvt_pk_bf16_f32 v182, v228, v229
	v_lshlrev_b32_e32 v228, 16, v87
	v_and_b32_e32 v229, s28, v87
	v_mul_f32_e32 v228, v228, v170
	v_mul_f32_e32 v229, v229, v171
	v_cvt_pk_bf16_f32 v183, v228, v229
	s_nop 1
	v_mfma_f32_16x16x32_bf16 v[188:191], v[100:103], v[180:183], v[188:191]
	v_mfma_f32_16x16x32_bf16 v[192:195], v[104:107], v[180:183], v[192:195]
	v_mfma_f32_16x16x32_bf16 v[200:203], v[108:111], v[180:183], v[200:203]
	v_mfma_f32_16x16x32_bf16 v[222:225], v[112:115], v[180:183], v[222:225]
	ds_read_b128 v[164:167], v233 offset:256
	ds_read_b128 v[168:171], v233 offset:272
	s_waitcnt lgkmcnt(2)
	v_lshlrev_b32_e32 v228, 16, v88
	v_and_b32_e32 v229, s28, v88
	v_mul_f32_e32 v228, v228, v172
	v_mul_f32_e32 v229, v229, v173
	v_cvt_pk_bf16_f32 v184, v228, v229
	v_lshlrev_b32_e32 v228, 16, v89
	v_and_b32_e32 v229, s28, v89
	v_mul_f32_e32 v228, v228, v174
	v_mul_f32_e32 v229, v229, v175
	v_cvt_pk_bf16_f32 v185, v228, v229
	v_lshlrev_b32_e32 v228, 16, v90
	v_and_b32_e32 v229, s28, v90
	v_mul_f32_e32 v228, v228, v176
	v_mul_f32_e32 v229, v229, v177
	v_cvt_pk_bf16_f32 v186, v228, v229
	v_lshlrev_b32_e32 v228, 16, v91
	v_and_b32_e32 v229, s28, v91
	v_mul_f32_e32 v228, v228, v178
	v_mul_f32_e32 v229, v229, v179
	v_cvt_pk_bf16_f32 v187, v228, v229
	s_nop 1
	v_mfma_f32_16x16x32_bf16 v[188:191], v[116:119], v[184:187], v[188:191]
	v_mfma_f32_16x16x32_bf16 v[192:195], v[120:123], v[184:187], v[192:195]
	v_mfma_f32_16x16x32_bf16 v[200:203], v[124:127], v[184:187], v[200:203]
	v_mfma_f32_16x16x32_bf16 v[222:225], v[128:131], v[184:187], v[222:225]
	ds_read_b128 v[172:175], v233 offset:384
	ds_read_b128 v[176:179], v233 offset:400
	s_waitcnt lgkmcnt(2)
	v_lshlrev_b32_e32 v228, 16, v92
	v_and_b32_e32 v229, s28, v92
	v_mul_f32_e32 v228, v228, v164
	v_mul_f32_e32 v229, v229, v165
	v_cvt_pk_bf16_f32 v180, v228, v229
	v_lshlrev_b32_e32 v228, 16, v93
	v_and_b32_e32 v229, s28, v93
	v_mul_f32_e32 v228, v228, v166
	v_mul_f32_e32 v229, v229, v167
	v_cvt_pk_bf16_f32 v181, v228, v229
	v_lshlrev_b32_e32 v228, 16, v94
	v_and_b32_e32 v229, s28, v94
	v_mul_f32_e32 v228, v228, v168
	v_mul_f32_e32 v229, v229, v169
	v_cvt_pk_bf16_f32 v182, v228, v229
	v_lshlrev_b32_e32 v228, 16, v95
	v_and_b32_e32 v229, s28, v95
	v_mul_f32_e32 v228, v228, v170
	v_mul_f32_e32 v229, v229, v171
	v_cvt_pk_bf16_f32 v183, v228, v229
	s_nop 1
	v_mfma_f32_16x16x32_bf16 v[188:191], v[132:135], v[180:183], v[188:191]
	v_mfma_f32_16x16x32_bf16 v[192:195], v[136:139], v[180:183], v[192:195]
	v_mfma_f32_16x16x32_bf16 v[200:203], v[140:143], v[180:183], v[200:203]
	v_mfma_f32_16x16x32_bf16 v[222:225], v[144:147], v[180:183], v[222:225]
	s_waitcnt lgkmcnt(0)
	v_lshlrev_b32_e32 v228, 16, v96
	v_and_b32_e32 v229, s28, v96
	v_mul_f32_e32 v228, v228, v172
	v_mul_f32_e32 v229, v229, v173
	v_cvt_pk_bf16_f32 v184, v228, v229
	v_lshlrev_b32_e32 v228, 16, v97
	v_and_b32_e32 v229, s28, v97
	v_mul_f32_e32 v228, v228, v174
	v_mul_f32_e32 v229, v229, v175
	v_cvt_pk_bf16_f32 v185, v228, v229
	v_lshlrev_b32_e32 v228, 16, v98
	v_and_b32_e32 v229, s28, v98
	v_mul_f32_e32 v228, v228, v176
	v_mul_f32_e32 v229, v229, v177
	v_cvt_pk_bf16_f32 v186, v228, v229
	v_lshlrev_b32_e32 v228, 16, v99
	v_and_b32_e32 v229, s28, v99
	v_mul_f32_e32 v228, v228, v178
	v_mul_f32_e32 v229, v229, v179
	v_cvt_pk_bf16_f32 v187, v228, v229
	s_nop 1
	v_mfma_f32_16x16x32_bf16 v[188:191], v[148:151], v[184:187], v[188:191]
	v_mfma_f32_16x16x32_bf16 v[192:195], v[152:155], v[184:187], v[192:195]
	v_mfma_f32_16x16x32_bf16 v[200:203], v[156:159], v[184:187], v[200:203]
	v_mfma_f32_16x16x32_bf16 v[222:225], v[160:163], v[184:187], v[222:225]
	s_nop 7
	v_readlane_b32 s58, v237, 7
	v_readlane_b32 s59, v237, 8
	s_lshl_b32 s100, s52, 15
	s_lshl_b32 s53, s42, 13
	s_add_u32 s100, s100, s53
	s_lshl_b32 s53, s43, 6
	s_add_u32 s100, s100, s53
	s_add_u32 s100, s100, 0x1800000
	s_add_u32 s58, s58, s100
	s_addc_u32 s59, s59, 0
	s_nop 3
	global_store_dwordx4 v205, v[188:191], s[58:59]
	global_store_dwordx4 v205, v[192:195], s[58:59] offset:64
	global_store_dwordx4 v205, v[200:203], s[58:59] offset:128
	global_store_dwordx4 v205, v[222:225], s[58:59] offset:192
	s_branch .Lsp3_done

.LBB0_561:
	s_andn2_b64 vcc, exec, s[38:39]
	s_cbranch_vccnz .LBB0_763
	v_readlane_b32 s4, v235, 63
	s_cmp_lt_i32 s4, 2
	s_mov_b64 s[38:39], -1
	s_cbranch_scc1 .LBB0_705
	s_lshl_b32 s62, s36, 5
	s_lshl_b32 s18, s36, 4
	v_readlane_b32 s4, v235, 63
	s_cmp_gt_i32 s4, 2
	s_cbranch_scc0 .LBB0_637
	s_branch .LBB0_636
